# speedup vs baseline: 1.0148x; 1.0102x over previous
; #define PG8_STAGE(bufoff, gbase, voff) do { _Pragma("unroll") for (int _i = 0; _i < 2; ++_i) \
;         __builtin_amdgcn_global_load_lds((const unsigned*)((const char*)(gbase) + (voff)[_i]), (PG8_LAS unsigned*)(lds + (bufoff) + ldsw + _i * 8192), 16, 0, 0); } while (0)
; #define PG8_LDA(dst, b, h) do { _Pragma("unroll") for (int m = 0; m < 4; ++m) _Pragma("unroll") for (int k = 0; k < 2; ++k) dst[m][k] = *(const PG8_LAS bf16x8*)(lds + PG8_SA(b, h) + aoff + m * 2048 + k * 1024); } while (0)
; #define PG8_LDB(dst, b, h) do { _Pragma("unroll") for (int n = 0; n < 2; ++n) _Pragma("unroll") for (int k = 0; k < 2; ++k) dst[n][k] = *(const PG8_LAS bf16x8*)(lds + PG8_SB(b, h) + boff + n * 2048 + k * 1024); } while (0)
; #define PG8_MMA(ai, bj, At, Bt) do { __builtin_amdgcn_s_setprio(1); _Pragma("unroll") for (int m = 0; m < 4; ++m) _Pragma("unroll") for (int n = 0; n < 2; ++n) _Pragma("unroll") for (int k = 0; k < 2; ++k) \
;         acc[ai][bj][m][n] = __builtin_amdgcn_mfma_f32_16x16x32_bf16(Bt[n][k], At[m][k], acc[ai][bj][m][n], 0, 0, 0); __builtin_amdgcn_s_setprio(0); } while (0)
; #define PG8_WAIT_V(n) asm volatile("s_waitcnt vmcnt(" #n ")" ::: "memory")
; #define PG8_WAIT_L(n) asm volatile("s_waitcnt lgkmcnt(" #n ")" ::: "memory")
; #define PG8_BAR __builtin_amdgcn_s_barrier()
; #define PG8_SCHED __builtin_amdgcn_sched_barrier(0)
; template <class Epi, class Sched, bool ALIGN_EPI = false, bool SP2 = false>
; __device__ __forceinline__ void gemm_phase(PG8_LAS unsigned char* lds, const Gemm g, const Sched& S, const Epi& E, int wv) {
;     ...
;             PG8_LDB(B0, 0, 0); PG8_LDB(B1, 0, 1); PG8_SCHED; PG8_LDA(At, 0, 0); PG8_STAGE(PG8_SA(1, 1), a1 + hstepA, voffA);
;             PG8_WAIT_V(8); PG8_WAIT_L(0); PG8_BAR; PG8_MMA(0, 0, At, B0); PG8_MMA(0, 1, At, B1); PG8_BAR; PG8_SCHED;
;             PG8_LDA(At, 0, 1); PG8_STAGE(PG8_SB(0, 0), b2, voffB); PG8_STAGE(PG8_SB(0, 1), b2 + hstepB, voffB); PG8_STAGE(PG8_SA(0, 0), a2, voffA);
;             PG8_WAIT_V(8); PG8_WAIT_L(0); PG8_BAR; PG8_MMA(1, 0, At, B0); PG8_MMA(1, 1, At, B1); PG8_BAR; PG8_SCHED;
.LBB0_59:
	s_add_u32 s0, s12, 0x100
	s_addc_u32 s1, s13, 0
	s_add_i32 s96, 0, 0x10000
	s_cmp_eq_u32 s79, 60
	s_cselect_b32 s17, s9, s1
	s_cselect_b32 s16, s8, s0
	v_add_u32_e32 v142, s96, v145
	s_cselect_b32 s15, s7, s77
	s_cselect_b32 s14, s75, s76
	s_add_i32 s97, 0, 0x14000
	ds_read_b128 v[158:161], v142
	ds_read_b128 v[162:165], v142 offset:1024
	ds_read_b128 v[166:169], v142 offset:2048
	ds_read_b128 v[170:173], v142 offset:3072
	v_add_u32_e32 v142, s97, v145
	ds_read_b128 v[174:177], v142
	ds_read_b128 v[178:181], v142 offset:1024
	ds_read_b128 v[182:185], v142 offset:2048
	ds_read_b128 v[186:189], v142 offset:3072
	v_lshl_add_u64 v[142:143], s[12:13], 0, v[138:139]
	s_add_i32 m0, s31, 0xc000
	ds_read_b128 v[190:193], v153
	ds_read_b128 v[198:201], v153 offset:1024
	ds_read_b128 v[218:221], v153 offset:2048
	ds_read_b128 v[222:225], v153 offset:3072
	ds_read_b128 v[226:229], v153 offset:4096
	ds_read_b128 v[230:233], v153 offset:5120
	ds_read_b128 v[234:237], v153 offset:6144
	ds_read_b128 v[238:241], v153 offset:7168
	global_load_lds_dwordx4 v[142:143], off
	v_lshl_add_u64 v[142:143], s[12:13], 0, v[140:141]
	s_add_i32 m0, s31, 0xe000
	s_nop 0
	global_load_lds_dwordx4 v[142:143], off
	s_waitcnt vmcnt(8)
	s_waitcnt lgkmcnt(0)
	s_barrier
	s_setprio 1
	s_waitcnt lgkmcnt(0)
	v_mfma_f32_16x16x32_bf16 v[126:129], v[158:161], v[190:193], v[126:129]
	v_mfma_f32_16x16x32_bf16 v[122:125], v[166:169], v[190:193], v[122:125]
	v_mfma_f32_16x16x32_bf16 v[118:121], v[158:161], v[218:221], v[118:121]
	v_mfma_f32_16x16x32_bf16 v[110:113], v[166:169], v[218:221], v[110:113]
	v_mfma_f32_16x16x32_bf16 v[102:105], v[158:161], v[226:229], v[102:105]
	v_mfma_f32_16x16x32_bf16 v[94:97], v[166:169], v[226:229], v[94:97]
	v_mfma_f32_16x16x32_bf16 v[86:89], v[158:161], v[234:237], v[86:89]
	v_mfma_f32_16x16x32_bf16 v[78:81], v[166:169], v[234:237], v[78:81]
	v_mfma_f32_16x16x32_bf16 v[126:129], v[162:165], v[198:201], v[126:129]
	v_mfma_f32_16x16x32_bf16 v[122:125], v[170:173], v[198:201], v[122:125]
	v_mfma_f32_16x16x32_bf16 v[118:121], v[162:165], v[222:225], v[118:121]
	v_mfma_f32_16x16x32_bf16 v[110:113], v[170:173], v[222:225], v[110:113]
	v_mfma_f32_16x16x32_bf16 v[102:105], v[162:165], v[230:233], v[102:105]
	v_mfma_f32_16x16x32_bf16 v[94:97], v[170:173], v[230:233], v[94:97]
	v_mfma_f32_16x16x32_bf16 v[86:89], v[162:165], v[238:241], v[86:89]
	v_mfma_f32_16x16x32_bf16 v[78:81], v[170:173], v[238:241], v[78:81]
	v_mfma_f32_16x16x32_bf16 v[114:117], v[174:177], v[190:193], v[114:117]
	v_mfma_f32_16x16x32_bf16 v[106:109], v[182:185], v[190:193], v[106:109]
	v_mfma_f32_16x16x32_bf16 v[98:101], v[174:177], v[218:221], v[98:101]
	v_mfma_f32_16x16x32_bf16 v[90:93], v[182:185], v[218:221], v[90:93]
	v_mfma_f32_16x16x32_bf16 v[82:85], v[174:177], v[226:229], v[82:85]
	v_mfma_f32_16x16x32_bf16 v[74:77], v[182:185], v[226:229], v[74:77]
	v_mfma_f32_16x16x32_bf16 v[70:73], v[174:177], v[234:237], v[70:73]
	v_mfma_f32_16x16x32_bf16 v[66:69], v[182:185], v[234:237], v[66:69]
	v_mfma_f32_16x16x32_bf16 v[114:117], v[178:181], v[198:201], v[114:117]
	v_mfma_f32_16x16x32_bf16 v[106:109], v[186:189], v[198:201], v[106:109]
	v_mfma_f32_16x16x32_bf16 v[98:101], v[178:181], v[222:225], v[98:101]
	v_mfma_f32_16x16x32_bf16 v[90:93], v[186:189], v[222:225], v[90:93]
	v_mfma_f32_16x16x32_bf16 v[82:85], v[178:181], v[230:233], v[82:85]
	v_mfma_f32_16x16x32_bf16 v[74:77], v[186:189], v[230:233], v[74:77]
	v_mfma_f32_16x16x32_bf16 v[70:73], v[178:181], v[238:241], v[70:73]
	v_mfma_f32_16x16x32_bf16 v[66:69], v[186:189], v[238:241], v[66:69]
	s_setprio 0
	s_barrier
	s_add_i32 s12, s96, s30
	v_lshl_add_u64 v[142:143], s[14:15], 0, v[132:133]
	s_mov_b32 m0, s12
	ds_read_b128 v[190:193], v153 offset:16384
	ds_read_b128 v[198:201], v153 offset:17408
	ds_read_b128 v[218:221], v153 offset:18432
	ds_read_b128 v[222:225], v153 offset:19456
	ds_read_b128 v[226:229], v153 offset:20480
	ds_read_b128 v[230:233], v153 offset:21504
	ds_read_b128 v[234:237], v153 offset:22528
	ds_read_b128 v[238:241], v153 offset:23552
	global_load_lds_dwordx4 v[142:143], off
	s_add_i32 m0, s12, 0x2000
	s_add_u32 s12, s14, 0x100000
	v_lshl_add_u64 v[154:155], s[14:15], 0, v[136:137]
	s_addc_u32 s13, s15, 0
	s_add_i32 s96, s97, s30
	global_load_lds_dwordx4 v[154:155], off
	v_lshl_add_u64 v[194:195], s[12:13], 0, v[132:133]
	s_mov_b32 m0, s96
	v_lshl_add_u64 v[196:197], s[16:17], 0, v[134:135]
	global_load_lds_dwordx4 v[194:195], off
	v_lshl_add_u64 v[194:195], s[12:13], 0, v[136:137]
	s_add_i32 m0, s96, 0x2000
	s_nop 0
	global_load_lds_dwordx4 v[194:195], off
	v_lshl_add_u64 v[194:195], s[16:17], 0, v[130:131]
	s_mov_b32 m0, s31
	s_nop 0
	global_load_lds_dwordx4 v[194:195], off
	s_mov_b32 m0, s33
	s_nop 0
	global_load_lds_dwordx4 v[196:197], off
	s_waitcnt vmcnt(8)
	s_waitcnt lgkmcnt(0)
	s_barrier
; #define PG8_STAGE(bufoff, gbase, voff) do { _Pragma("unroll") for (int _i = 0; _i < 2; ++_i) \
;         __builtin_amdgcn_global_load_lds((const unsigned*)((const char*)(gbase) + (voff)[_i]), (PG8_LAS unsigned*)(lds + (bufoff) + ldsw + _i * 8192), 16, 0, 0); } while (0)
; #define PG8_LDA(dst, b, h) do { _Pragma("unroll") for (int m = 0; m < 4; ++m) _Pragma("unroll") for (int k = 0; k < 2; ++k) dst[m][k] = *(const PG8_LAS bf16x8*)(lds + PG8_SA(b, h) + aoff + m * 2048 + k * 1024); } while (0)
; #define PG8_LDB(dst, b, h) do { _Pragma("unroll") for (int n = 0; n < 2; ++n) _Pragma("unroll") for (int k = 0; k < 2; ++k) dst[n][k] = *(const PG8_LAS bf16x8*)(lds + PG8_SB(b, h) + boff + n * 2048 + k * 1024); } while (0)
; #define PG8_MMA(ai, bj, At, Bt) do { __builtin_amdgcn_s_setprio(1); _Pragma("unroll") for (int m = 0; m < 4; ++m) _Pragma("unroll") for (int n = 0; n < 2; ++n) _Pragma("unroll") for (int k = 0; k < 2; ++k) \
;         acc[ai][bj][m][n] = __builtin_amdgcn_mfma_f32_16x16x32_bf16(Bt[n][k], At[m][k], acc[ai][bj][m][n], 0, 0, 0); __builtin_amdgcn_s_setprio(0); } while (0)
; #define PG8_WAIT_V(n) asm volatile("s_waitcnt vmcnt(" #n ")" ::: "memory")
; #define PG8_WAIT_L(n) asm volatile("s_waitcnt lgkmcnt(" #n ")" ::: "memory")
; #define PG8_BAR __builtin_amdgcn_s_barrier()
; #define PG8_SCHED __builtin_amdgcn_sched_barrier(0)
; template <class Epi, class Sched, bool ALIGN_EPI = false, bool SP2 = false>
; __device__ __forceinline__ void gemm_phase(PG8_LAS unsigned char* lds, const Gemm g, const Sched& S, const Epi& E, int wv) {
;     ...
;             PG8_WAIT_V(8); PG8_WAIT_L(0); PG8_BAR; PG8_MMA(1, 0, At, B0); PG8_MMA(1, 1, At, B1); PG8_BAR; PG8_SCHED;
;             PG8_LDB(B0, 1, 0); PG8_LDB(B1, 1, 1); PG8_SCHED; PG8_LDA(At, 1, 0); PG8_STAGE(PG8_SA(0, 1), a2 + hstepA, voffA);
;             PG8_WAIT_V(8); PG8_WAIT_L(0); PG8_BAR; PG8_MMA(0, 0, At, B0); PG8_MMA(0, 1, At, B1); PG8_BAR; PG8_SCHED;
	s_setprio 1
	s_waitcnt lgkmcnt(0)
	v_mfma_f32_16x16x32_bf16 v[62:65], v[158:161], v[190:193], v[62:65]
	v_mfma_f32_16x16x32_bf16 v[58:61], v[166:169], v[190:193], v[58:61]
	v_mfma_f32_16x16x32_bf16 v[54:57], v[158:161], v[218:221], v[54:57]
	v_mfma_f32_16x16x32_bf16 v[46:49], v[166:169], v[218:221], v[46:49]
	v_mfma_f32_16x16x32_bf16 v[38:41], v[158:161], v[226:229], v[38:41]
	v_mfma_f32_16x16x32_bf16 v[30:33], v[166:169], v[226:229], v[30:33]
	v_mfma_f32_16x16x32_bf16 v[22:25], v[158:161], v[234:237], v[22:25]
	v_mfma_f32_16x16x32_bf16 v[14:17], v[166:169], v[234:237], v[14:17]
	v_mfma_f32_16x16x32_bf16 v[62:65], v[162:165], v[198:201], v[62:65]
	v_mfma_f32_16x16x32_bf16 v[58:61], v[170:173], v[198:201], v[58:61]
	v_mfma_f32_16x16x32_bf16 v[54:57], v[162:165], v[222:225], v[54:57]
	v_mfma_f32_16x16x32_bf16 v[46:49], v[170:173], v[222:225], v[46:49]
	v_mfma_f32_16x16x32_bf16 v[38:41], v[162:165], v[230:233], v[38:41]
	v_mfma_f32_16x16x32_bf16 v[30:33], v[170:173], v[230:233], v[30:33]
	v_mfma_f32_16x16x32_bf16 v[22:25], v[162:165], v[238:241], v[22:25]
	v_mfma_f32_16x16x32_bf16 v[14:17], v[170:173], v[238:241], v[14:17]
	v_mfma_f32_16x16x32_bf16 v[50:53], v[174:177], v[190:193], v[50:53]
	v_mfma_f32_16x16x32_bf16 v[42:45], v[182:185], v[190:193], v[42:45]
	v_mfma_f32_16x16x32_bf16 v[34:37], v[174:177], v[218:221], v[34:37]
	v_mfma_f32_16x16x32_bf16 v[26:29], v[182:185], v[218:221], v[26:29]
	v_mfma_f32_16x16x32_bf16 v[18:21], v[174:177], v[226:229], v[18:21]
	v_mfma_f32_16x16x32_bf16 v[10:13], v[182:185], v[226:229], v[10:13]
	v_mfma_f32_16x16x32_bf16 v[6:9], v[174:177], v[234:237], v[6:9]
	v_mfma_f32_16x16x32_bf16 v[2:5], v[182:185], v[234:237], v[2:5]
	v_mfma_f32_16x16x32_bf16 v[50:53], v[178:181], v[198:201], v[50:53]
	v_mfma_f32_16x16x32_bf16 v[42:45], v[186:189], v[198:201], v[42:45]
	v_mfma_f32_16x16x32_bf16 v[34:37], v[178:181], v[222:225], v[34:37]
	v_mfma_f32_16x16x32_bf16 v[26:29], v[186:189], v[222:225], v[26:29]
	v_mfma_f32_16x16x32_bf16 v[18:21], v[178:181], v[230:233], v[18:21]
	v_mfma_f32_16x16x32_bf16 v[10:13], v[186:189], v[230:233], v[10:13]
	v_mfma_f32_16x16x32_bf16 v[6:9], v[178:181], v[238:241], v[6:9]
	v_mfma_f32_16x16x32_bf16 v[2:5], v[186:189], v[238:241], v[2:5]
	s_setprio 0
	s_barrier
	s_add_i32 s96, 0, 0x18000
	v_add_u32_e32 v157, s96, v145
	s_add_i32 s97, 0, 0x1c000
	ds_read_b128 v[158:161], v157
	ds_read_b128 v[162:165], v157 offset:1024
	ds_read_b128 v[166:169], v157 offset:2048
	ds_read_b128 v[170:173], v157 offset:3072
	v_add_u32_e32 v157, s97, v145
	ds_read_b128 v[174:177], v157
	ds_read_b128 v[178:181], v157 offset:1024
	ds_read_b128 v[182:185], v157 offset:2048
	ds_read_b128 v[186:189], v157 offset:3072
	s_add_u32 s12, s16, 0x2c0000
	s_addc_u32 s13, s17, 0
	s_mov_b32 m0, s40
	v_lshl_add_u64 v[202:203], s[12:13], 0, v[130:131]
	ds_read_b128 v[190:193], v153 offset:32768
	ds_read_b128 v[198:201], v153 offset:33792
	ds_read_b128 v[218:221], v153 offset:34816
	ds_read_b128 v[222:225], v153 offset:35840
	ds_read_b128 v[226:229], v153 offset:36864
	ds_read_b128 v[230:233], v153 offset:37888
	ds_read_b128 v[234:237], v153 offset:38912
	ds_read_b128 v[238:241], v153 offset:39936
	global_load_lds_dwordx4 v[202:203], off
	v_lshl_add_u64 v[202:203], s[12:13], 0, v[134:135]
	s_mov_b32 m0, s41
	s_nop 0
	global_load_lds_dwordx4 v[202:203], off
	s_waitcnt vmcnt(8)
	s_waitcnt lgkmcnt(0)
	s_barrier
	s_setprio 1
	s_waitcnt lgkmcnt(0)
	v_mfma_f32_16x16x32_bf16 v[126:129], v[158:161], v[190:193], v[126:129]
	v_mfma_f32_16x16x32_bf16 v[122:125], v[166:169], v[190:193], v[122:125]
	v_mfma_f32_16x16x32_bf16 v[118:121], v[158:161], v[218:221], v[118:121]
	v_mfma_f32_16x16x32_bf16 v[110:113], v[166:169], v[218:221], v[110:113]
	v_mfma_f32_16x16x32_bf16 v[102:105], v[158:161], v[226:229], v[102:105]
	v_mfma_f32_16x16x32_bf16 v[94:97], v[166:169], v[226:229], v[94:97]
	v_mfma_f32_16x16x32_bf16 v[86:89], v[158:161], v[234:237], v[86:89]
	v_mfma_f32_16x16x32_bf16 v[78:81], v[166:169], v[234:237], v[78:81]
	v_mfma_f32_16x16x32_bf16 v[126:129], v[162:165], v[198:201], v[126:129]
	v_mfma_f32_16x16x32_bf16 v[122:125], v[170:173], v[198:201], v[122:125]
	v_mfma_f32_16x16x32_bf16 v[118:121], v[162:165], v[222:225], v[118:121]
	v_mfma_f32_16x16x32_bf16 v[110:113], v[170:173], v[222:225], v[110:113]
	v_mfma_f32_16x16x32_bf16 v[102:105], v[162:165], v[230:233], v[102:105]
	v_mfma_f32_16x16x32_bf16 v[94:97], v[170:173], v[230:233], v[94:97]
	v_mfma_f32_16x16x32_bf16 v[86:89], v[162:165], v[238:241], v[86:89]
	v_mfma_f32_16x16x32_bf16 v[78:81], v[170:173], v[238:241], v[78:81]
	v_mfma_f32_16x16x32_bf16 v[114:117], v[174:177], v[190:193], v[114:117]
	v_mfma_f32_16x16x32_bf16 v[106:109], v[182:185], v[190:193], v[106:109]
	v_mfma_f32_16x16x32_bf16 v[98:101], v[174:177], v[218:221], v[98:101]
	v_mfma_f32_16x16x32_bf16 v[90:93], v[182:185], v[218:221], v[90:93]
	v_mfma_f32_16x16x32_bf16 v[82:85], v[174:177], v[226:229], v[82:85]
	v_mfma_f32_16x16x32_bf16 v[74:77], v[182:185], v[226:229], v[74:77]
	v_mfma_f32_16x16x32_bf16 v[70:73], v[174:177], v[234:237], v[70:73]
	v_mfma_f32_16x16x32_bf16 v[66:69], v[182:185], v[234:237], v[66:69]
	v_mfma_f32_16x16x32_bf16 v[114:117], v[178:181], v[198:201], v[114:117]
	v_mfma_f32_16x16x32_bf16 v[106:109], v[186:189], v[198:201], v[106:109]
	v_mfma_f32_16x16x32_bf16 v[98:101], v[178:181], v[222:225], v[98:101]
	v_mfma_f32_16x16x32_bf16 v[90:93], v[186:189], v[222:225], v[90:93]
	v_mfma_f32_16x16x32_bf16 v[82:85], v[178:181], v[230:233], v[82:85]
	v_mfma_f32_16x16x32_bf16 v[74:77], v[186:189], v[230:233], v[74:77]
	v_mfma_f32_16x16x32_bf16 v[70:73], v[178:181], v[238:241], v[70:73]
	v_mfma_f32_16x16x32_bf16 v[66:69], v[186:189], v[238:241], v[66:69]
	s_setprio 0
	s_barrier
; #define PG8_STAGE(bufoff, gbase, voff) do { _Pragma("unroll") for (int _i = 0; _i < 2; ++_i) \
;         __builtin_amdgcn_global_load_lds((const unsigned*)((const char*)(gbase) + (voff)[_i]), (PG8_LAS unsigned*)(lds + (bufoff) + ldsw + _i * 8192), 16, 0, 0); } while (0)
; #define PG8_LDA(dst, b, h) do { _Pragma("unroll") for (int m = 0; m < 4; ++m) _Pragma("unroll") for (int k = 0; k < 2; ++k) dst[m][k] = *(const PG8_LAS bf16x8*)(lds + PG8_SA(b, h) + aoff + m * 2048 + k * 1024); } while (0)
; #define PG8_MMA(ai, bj, At, Bt) do { __builtin_amdgcn_s_setprio(1); _Pragma("unroll") for (int m = 0; m < 4; ++m) _Pragma("unroll") for (int n = 0; n < 2; ++n) _Pragma("unroll") for (int k = 0; k < 2; ++k) \
;         acc[ai][bj][m][n] = __builtin_amdgcn_mfma_f32_16x16x32_bf16(Bt[n][k], At[m][k], acc[ai][bj][m][n], 0, 0, 0); __builtin_amdgcn_s_setprio(0); } while (0)
; #define PG8_WAIT_V(n) asm volatile("s_waitcnt vmcnt(" #n ")" ::: "memory")
; #define PG8_WAIT_L(n) asm volatile("s_waitcnt lgkmcnt(" #n ")" ::: "memory")
; #define PG8_BAR __builtin_amdgcn_s_barrier()
; #define PG8_SCHED __builtin_amdgcn_sched_barrier(0)
; template <class Epi, class Sched, bool ALIGN_EPI = false, bool SP2 = false>
; __device__ __forceinline__ void gemm_phase(PG8_LAS unsigned char* lds, const Gemm g, const Sched& S, const Epi& E, int wv) {
;     ...
;         for (int t = 0; t < nt; t += 2) {
;             const bool last = (t == nt - 2);
;     ...
;             PG8_LDA(At, 1, 1); PG8_STAGE(PG8_SB(1, 0), b3, voffB); PG8_STAGE(PG8_SB(1, 1), b3 + hstepB, voffB); PG8_STAGE(PG8_SA(1, 0), a3, voffA);
;             PG8_WAIT_V(8); PG8_WAIT_L(0); PG8_BAR; PG8_MMA(1, 0, At, B0); PG8_MMA(1, 1, At, B1); PG8_BAR; PG8_SCHED;
	s_add_i32 s12, s96, s30
	v_lshl_add_u64 v[142:143], v[142:143], 0, s[20:21]
	s_mov_b32 m0, s12
	ds_read_b128 v[190:193], v153 offset:49152
	ds_read_b128 v[198:201], v153 offset:50176
	ds_read_b128 v[218:221], v153 offset:51200
	ds_read_b128 v[222:225], v153 offset:52224
	ds_read_b128 v[226:229], v153 offset:53248
	ds_read_b128 v[230:233], v153 offset:54272
	ds_read_b128 v[234:237], v153 offset:55296
	ds_read_b128 v[238:241], v153 offset:56320
	global_load_lds_dwordx4 v[142:143], off
	s_add_i32 m0, s12, 0x2000
	s_add_u32 s12, s14, 0x100080
	v_lshl_add_u64 v[142:143], v[154:155], 0, s[20:21]
	s_addc_u32 s13, s15, 0
	s_add_i32 s14, s97, s30
	global_load_lds_dwordx4 v[142:143], off
	v_lshl_add_u64 v[142:143], s[12:13], 0, v[132:133]
	s_mov_b32 m0, s14
	s_nop 0
	global_load_lds_dwordx4 v[142:143], off
	v_lshl_add_u64 v[142:143], s[12:13], 0, v[136:137]
	s_add_i32 m0, s14, 0x2000
	s_nop 0
	global_load_lds_dwordx4 v[142:143], off
	v_lshl_add_u64 v[142:143], v[194:195], 0, s[20:21]
	s_mov_b32 m0, s43
	s_nop 0
	global_load_lds_dwordx4 v[142:143], off
	v_lshl_add_u64 v[142:143], v[196:197], 0, s[20:21]
	s_mov_b32 m0, s65
	s_nop 0
	global_load_lds_dwordx4 v[142:143], off
	s_waitcnt vmcnt(8)
	s_waitcnt lgkmcnt(0)
	s_barrier
	s_setprio 1
	s_waitcnt lgkmcnt(0)
	v_mfma_f32_16x16x32_bf16 v[62:65], v[158:161], v[190:193], v[62:65]
	v_mfma_f32_16x16x32_bf16 v[58:61], v[166:169], v[190:193], v[58:61]
	v_mfma_f32_16x16x32_bf16 v[54:57], v[158:161], v[218:221], v[54:57]
	v_mfma_f32_16x16x32_bf16 v[46:49], v[166:169], v[218:221], v[46:49]
	v_mfma_f32_16x16x32_bf16 v[38:41], v[158:161], v[226:229], v[38:41]
	v_mfma_f32_16x16x32_bf16 v[30:33], v[166:169], v[226:229], v[30:33]
	v_mfma_f32_16x16x32_bf16 v[22:25], v[158:161], v[234:237], v[22:25]
	v_mfma_f32_16x16x32_bf16 v[14:17], v[166:169], v[234:237], v[14:17]
	v_mfma_f32_16x16x32_bf16 v[62:65], v[162:165], v[198:201], v[62:65]
	v_mfma_f32_16x16x32_bf16 v[58:61], v[170:173], v[198:201], v[58:61]
	v_mfma_f32_16x16x32_bf16 v[54:57], v[162:165], v[222:225], v[54:57]
	v_mfma_f32_16x16x32_bf16 v[46:49], v[170:173], v[222:225], v[46:49]
	v_mfma_f32_16x16x32_bf16 v[38:41], v[162:165], v[230:233], v[38:41]
	v_mfma_f32_16x16x32_bf16 v[30:33], v[170:173], v[230:233], v[30:33]
	v_mfma_f32_16x16x32_bf16 v[22:25], v[162:165], v[238:241], v[22:25]
	v_mfma_f32_16x16x32_bf16 v[14:17], v[170:173], v[238:241], v[14:17]
	v_mfma_f32_16x16x32_bf16 v[50:53], v[174:177], v[190:193], v[50:53]
	v_mfma_f32_16x16x32_bf16 v[42:45], v[182:185], v[190:193], v[42:45]
	v_mfma_f32_16x16x32_bf16 v[34:37], v[174:177], v[218:221], v[34:37]
	v_mfma_f32_16x16x32_bf16 v[26:29], v[182:185], v[218:221], v[26:29]
	v_mfma_f32_16x16x32_bf16 v[18:21], v[174:177], v[226:229], v[18:21]
	v_mfma_f32_16x16x32_bf16 v[10:13], v[182:185], v[226:229], v[10:13]
	v_mfma_f32_16x16x32_bf16 v[6:9], v[174:177], v[234:237], v[6:9]
	v_mfma_f32_16x16x32_bf16 v[2:5], v[182:185], v[234:237], v[2:5]
	v_mfma_f32_16x16x32_bf16 v[50:53], v[178:181], v[198:201], v[50:53]
	v_mfma_f32_16x16x32_bf16 v[42:45], v[186:189], v[198:201], v[42:45]
	v_mfma_f32_16x16x32_bf16 v[34:37], v[178:181], v[222:225], v[34:37]
	v_mfma_f32_16x16x32_bf16 v[26:29], v[186:189], v[222:225], v[26:29]
	v_mfma_f32_16x16x32_bf16 v[18:21], v[178:181], v[230:233], v[18:21]
	v_mfma_f32_16x16x32_bf16 v[10:13], v[186:189], v[230:233], v[10:13]
	v_mfma_f32_16x16x32_bf16 v[6:9], v[178:181], v[238:241], v[6:9]
	v_mfma_f32_16x16x32_bf16 v[2:5], v[186:189], v[238:241], v[2:5]
	s_setprio 0
	s_barrier
	s_add_i32 s79, s79, 2
	s_add_u32 s76, s76, 0x100
	s_addc_u32 s77, s77, 0
	s_cmp_gt_u32 s79, 61
	s_mov_b64 s[12:13], s[0:1]
	s_cbranch_scc0 .LBB0_59
	s_and_b64 vcc, exec, s[4:5]
	s_cbranch_vccz .LBB0_62
	s_barrier

; #define PG8_STAGE(bufoff, gbase, voff) do { _Pragma("unroll") for (int _i = 0; _i < 2; ++_i) \
;         __builtin_amdgcn_global_load_lds((const unsigned*)((const char*)(gbase) + (voff)[_i]), (PG8_LAS unsigned*)(lds + (bufoff) + ldsw + _i * 8192), 16, 0, 0); } while (0)
; #define PG8_LDA(dst, b, h) do { _Pragma("unroll") for (int m = 0; m < 4; ++m) _Pragma("unroll") for (int k = 0; k < 2; ++k) dst[m][k] = *(const PG8_LAS bf16x8*)(lds + PG8_SA(b, h) + aoff + m * 2048 + k * 1024); } while (0)
; #define PG8_LDB(dst, b, h) do { _Pragma("unroll") for (int n = 0; n < 2; ++n) _Pragma("unroll") for (int k = 0; k < 2; ++k) dst[n][k] = *(const PG8_LAS bf16x8*)(lds + PG8_SB(b, h) + boff + n * 2048 + k * 1024); } while (0)
; #define PG8_MMA(ai, bj, At, Bt) do { __builtin_amdgcn_s_setprio(1); _Pragma("unroll") for (int m = 0; m < 4; ++m) _Pragma("unroll") for (int n = 0; n < 2; ++n) _Pragma("unroll") for (int k = 0; k < 2; ++k) \
;         acc[ai][bj][m][n] = __builtin_amdgcn_mfma_f32_16x16x32_bf16(Bt[n][k], At[m][k], acc[ai][bj][m][n], 0, 0, 0); __builtin_amdgcn_s_setprio(0); } while (0)
; #define PG8_WAIT_V(n) asm volatile("s_waitcnt vmcnt(" #n ")" ::: "memory")
; #define PG8_WAIT_L(n) asm volatile("s_waitcnt lgkmcnt(" #n ")" ::: "memory")
; #define PG8_BAR __builtin_amdgcn_s_barrier()
; #define PG8_SCHED __builtin_amdgcn_sched_barrier(0)
; template <class Epi, class Sched, bool ALIGN_EPI = false, bool SP2 = false>
; __device__ __forceinline__ void gemm_phase(PG8_LAS unsigned char* lds, const Gemm g, const Sched& S, const Epi& E, int wv) {
;     ...
;             const bool last = (t == nt - 2);
;             const char* a1 = cA + (size_t)(t + 1) * kstep;
;             const char* a2 = last ? nA : cA + (size_t)(t + 2) * kstep; const char* b2 = last ? nB : cB + (size_t)(t + 2) * kstep;
;             const char* a3 = a2 + kstep; const char* b3 = b2 + kstep;
;             if (last && has_next) S.a_ready(nxt);
;             if constexpr (SP2) {
;             PG8_LDB(B0, 0, 0); PG8_LDB(B1, 0, 1); PG8_SCHED; PG8_LDA(At, 0, 0); PG8_STAGE(PG8_SA(1, 1), a1 + hstepA, voffA);
;             PG8_WAIT_V(8); PG8_WAIT_L(0); PG8_BAR; PG8_MMA(0, 0, At, B0); PG8_MMA(0, 1, At, B1); PG8_BAR; PG8_SCHED;
;             PG8_LDA(At, 0, 1); PG8_STAGE(PG8_SB(0, 0), b2, voffB); PG8_STAGE(PG8_SB(0, 1), b2 + hstepB, voffB); PG8_STAGE(PG8_SA(0, 0), a2, voffA);
.LBB0_86:
	s_add_u32 s16, s14, 0xfffc0080
	s_addc_u32 s17, s15, -1
	s_add_i32 s96, 0, 0x10000
	s_cmp_eq_u32 s79, 12
	s_cselect_b32 s19, s7, s17
	s_cselect_b32 s18, s74, s16
	v_add_u32_e32 v142, s96, v145
	s_cselect_b32 s17, s5, s77
	s_cselect_b32 s16, s75, s76
	s_add_i32 vcc_lo, 0, 0x14000
	ds_read_b128 v[148:151], v142
	ds_read_b128 v[152:155], v142 offset:1024
	ds_read_b128 v[158:161], v142 offset:2048
	ds_read_b128 v[162:165], v142 offset:3072
	v_add_u32_e32 v142, vcc_lo, v145
	ds_read_b128 v[166:169], v142
	ds_read_b128 v[170:173], v142 offset:1024
	ds_read_b128 v[174:177], v142 offset:2048
	ds_read_b128 v[178:181], v142 offset:3072
	v_lshl_add_u64 v[142:143], s[14:15], 0, v[138:139]
	s_add_i32 m0, s40, 0xc000
	ds_read_b128 v[182:185], v146
	ds_read_b128 v[186:189], v146 offset:1024
	ds_read_b128 v[190:193], v146 offset:2048
	ds_read_b128 v[198:201], v146 offset:3072
	ds_read_b128 v[218:221], v146 offset:4096
	ds_read_b128 v[222:225], v146 offset:5120
	ds_read_b128 v[226:229], v146 offset:6144
	ds_read_b128 v[230:233], v146 offset:7168
	global_load_lds_dwordx4 v[142:143], off
	v_lshl_add_u64 v[142:143], s[14:15], 0, v[140:141]
	s_add_i32 m0, s40, 0xe000
	s_nop 0
	global_load_lds_dwordx4 v[142:143], off
	s_waitcnt vmcnt(8)
	s_waitcnt lgkmcnt(0)
	s_barrier
	s_setprio 1
	s_waitcnt lgkmcnt(0)
	v_mfma_f32_16x16x32_bf16 v[126:129], v[148:151], v[182:185], v[126:129]
	v_mfma_f32_16x16x32_bf16 v[122:125], v[158:161], v[182:185], v[122:125]
	v_mfma_f32_16x16x32_bf16 v[110:113], v[148:151], v[190:193], v[110:113]
	v_mfma_f32_16x16x32_bf16 v[106:109], v[158:161], v[190:193], v[106:109]
	v_mfma_f32_16x16x32_bf16 v[94:97], v[148:151], v[218:221], v[94:97]
	v_mfma_f32_16x16x32_bf16 v[90:93], v[158:161], v[218:221], v[90:93]
	v_mfma_f32_16x16x32_bf16 v[78:81], v[148:151], v[226:229], v[78:81]
	v_mfma_f32_16x16x32_bf16 v[74:77], v[158:161], v[226:229], v[74:77]
	v_mfma_f32_16x16x32_bf16 v[126:129], v[152:155], v[186:189], v[126:129]
	v_mfma_f32_16x16x32_bf16 v[122:125], v[162:165], v[186:189], v[122:125]
	v_mfma_f32_16x16x32_bf16 v[110:113], v[152:155], v[198:201], v[110:113]
	v_mfma_f32_16x16x32_bf16 v[106:109], v[162:165], v[198:201], v[106:109]
	v_mfma_f32_16x16x32_bf16 v[94:97], v[152:155], v[222:225], v[94:97]
	v_mfma_f32_16x16x32_bf16 v[90:93], v[162:165], v[222:225], v[90:93]
	v_mfma_f32_16x16x32_bf16 v[78:81], v[152:155], v[230:233], v[78:81]
	v_mfma_f32_16x16x32_bf16 v[74:77], v[162:165], v[230:233], v[74:77]
	v_mfma_f32_16x16x32_bf16 v[118:121], v[166:169], v[182:185], v[118:121]
	v_mfma_f32_16x16x32_bf16 v[114:117], v[174:177], v[182:185], v[114:117]
	v_mfma_f32_16x16x32_bf16 v[102:105], v[166:169], v[190:193], v[102:105]
	v_mfma_f32_16x16x32_bf16 v[98:101], v[174:177], v[190:193], v[98:101]
	v_mfma_f32_16x16x32_bf16 v[86:89], v[166:169], v[218:221], v[86:89]
	v_mfma_f32_16x16x32_bf16 v[82:85], v[174:177], v[218:221], v[82:85]
	v_mfma_f32_16x16x32_bf16 v[70:73], v[166:169], v[226:229], v[70:73]
	v_mfma_f32_16x16x32_bf16 v[66:69], v[174:177], v[226:229], v[66:69]
	v_mfma_f32_16x16x32_bf16 v[118:121], v[170:173], v[186:189], v[118:121]
	v_mfma_f32_16x16x32_bf16 v[114:117], v[178:181], v[186:189], v[114:117]
	v_mfma_f32_16x16x32_bf16 v[102:105], v[170:173], v[198:201], v[102:105]
	v_mfma_f32_16x16x32_bf16 v[98:101], v[178:181], v[198:201], v[98:101]
	v_mfma_f32_16x16x32_bf16 v[86:89], v[170:173], v[222:225], v[86:89]
	v_mfma_f32_16x16x32_bf16 v[82:85], v[178:181], v[222:225], v[82:85]
	v_mfma_f32_16x16x32_bf16 v[70:73], v[170:173], v[230:233], v[70:73]
	v_mfma_f32_16x16x32_bf16 v[66:69], v[178:181], v[230:233], v[66:69]
	s_setprio 0
	s_barrier
	s_add_i32 s96, s96, s33
	v_lshl_add_u64 v[142:143], s[16:17], 0, v[132:133]
	s_mov_b32 m0, s96
	ds_read_b128 v[182:185], v146 offset:16384
	ds_read_b128 v[186:189], v146 offset:17408
	ds_read_b128 v[190:193], v146 offset:18432
	ds_read_b128 v[198:201], v146 offset:19456
	ds_read_b128 v[218:221], v146 offset:20480
	ds_read_b128 v[222:225], v146 offset:21504
	ds_read_b128 v[226:229], v146 offset:22528
	ds_read_b128 v[230:233], v146 offset:23552
	global_load_lds_dwordx4 v[142:143], off
	s_add_i32 m0, s96, 0x2000
	s_add_u32 s96, s16, 0x40000
	v_lshl_add_u64 v[194:195], s[16:17], 0, v[136:137]
	s_addc_u32 s97, s17, 0
	s_add_i32 vcc_lo, vcc_lo, s33
	global_load_lds_dwordx4 v[194:195], off
	v_lshl_add_u64 v[196:197], s[96:97], 0, v[132:133]
	s_mov_b32 m0, vcc_lo
	v_lshl_add_u64 v[202:203], s[18:19], 0, v[134:135]
	global_load_lds_dwordx4 v[196:197], off
	v_lshl_add_u64 v[196:197], s[96:97], 0, v[136:137]
	s_add_i32 m0, vcc_lo, 0x2000
	s_nop 0
	global_load_lds_dwordx4 v[196:197], off
	v_lshl_add_u64 v[196:197], s[18:19], 0, v[130:131]
	s_mov_b32 m0, s40
	s_nop 0
	global_load_lds_dwordx4 v[196:197], off
	s_mov_b32 m0, s41
	s_nop 0
	global_load_lds_dwordx4 v[202:203], off
	s_waitcnt vmcnt(8)
	s_waitcnt lgkmcnt(0)
	s_barrier
; #define PG8_STAGE(bufoff, gbase, voff) do { _Pragma("unroll") for (int _i = 0; _i < 2; ++_i) \
;         __builtin_amdgcn_global_load_lds((const unsigned*)((const char*)(gbase) + (voff)[_i]), (PG8_LAS unsigned*)(lds + (bufoff) + ldsw + _i * 8192), 16, 0, 0); } while (0)
; #define PG8_LDA(dst, b, h) do { _Pragma("unroll") for (int m = 0; m < 4; ++m) _Pragma("unroll") for (int k = 0; k < 2; ++k) dst[m][k] = *(const PG8_LAS bf16x8*)(lds + PG8_SA(b, h) + aoff + m * 2048 + k * 1024); } while (0)
; #define PG8_LDB(dst, b, h) do { _Pragma("unroll") for (int n = 0; n < 2; ++n) _Pragma("unroll") for (int k = 0; k < 2; ++k) dst[n][k] = *(const PG8_LAS bf16x8*)(lds + PG8_SB(b, h) + boff + n * 2048 + k * 1024); } while (0)
; #define PG8_MMA(ai, bj, At, Bt) do { __builtin_amdgcn_s_setprio(1); _Pragma("unroll") for (int m = 0; m < 4; ++m) _Pragma("unroll") for (int n = 0; n < 2; ++n) _Pragma("unroll") for (int k = 0; k < 2; ++k) \
;         acc[ai][bj][m][n] = __builtin_amdgcn_mfma_f32_16x16x32_bf16(Bt[n][k], At[m][k], acc[ai][bj][m][n], 0, 0, 0); __builtin_amdgcn_s_setprio(0); } while (0)
; #define PG8_WAIT_V(n) asm volatile("s_waitcnt vmcnt(" #n ")" ::: "memory")
; #define PG8_WAIT_L(n) asm volatile("s_waitcnt lgkmcnt(" #n ")" ::: "memory")
; #define PG8_BAR __builtin_amdgcn_s_barrier()
; #define PG8_SCHED __builtin_amdgcn_sched_barrier(0)
; template <class Epi, class Sched, bool ALIGN_EPI = false, bool SP2 = false>
; __device__ __forceinline__ void gemm_phase(PG8_LAS unsigned char* lds, const Gemm g, const Sched& S, const Epi& E, int wv) {
;     ...
;             PG8_WAIT_V(8); PG8_WAIT_L(0); PG8_BAR; PG8_MMA(1, 0, At, B0); PG8_MMA(1, 1, At, B1); PG8_BAR; PG8_SCHED;
;             PG8_LDB(B0, 1, 0); PG8_LDB(B1, 1, 1); PG8_SCHED; PG8_LDA(At, 1, 0); PG8_STAGE(PG8_SA(0, 1), a2 + hstepA, voffA);
;             PG8_WAIT_V(8); PG8_WAIT_L(0); PG8_BAR; PG8_MMA(0, 0, At, B0); PG8_MMA(0, 1, At, B1); PG8_BAR; PG8_SCHED;
	s_setprio 1
	s_waitcnt lgkmcnt(0)
	v_mfma_f32_16x16x32_bf16 v[62:65], v[148:151], v[182:185], v[62:65]
	v_mfma_f32_16x16x32_bf16 v[58:61], v[158:161], v[182:185], v[58:61]
	v_mfma_f32_16x16x32_bf16 v[46:49], v[148:151], v[190:193], v[46:49]
	v_mfma_f32_16x16x32_bf16 v[42:45], v[158:161], v[190:193], v[42:45]
	v_mfma_f32_16x16x32_bf16 v[30:33], v[148:151], v[218:221], v[30:33]
	v_mfma_f32_16x16x32_bf16 v[26:29], v[158:161], v[218:221], v[26:29]
	v_mfma_f32_16x16x32_bf16 v[14:17], v[148:151], v[226:229], v[14:17]
	v_mfma_f32_16x16x32_bf16 v[10:13], v[158:161], v[226:229], v[10:13]
	v_mfma_f32_16x16x32_bf16 v[62:65], v[152:155], v[186:189], v[62:65]
	v_mfma_f32_16x16x32_bf16 v[58:61], v[162:165], v[186:189], v[58:61]
	v_mfma_f32_16x16x32_bf16 v[46:49], v[152:155], v[198:201], v[46:49]
	v_mfma_f32_16x16x32_bf16 v[42:45], v[162:165], v[198:201], v[42:45]
	v_mfma_f32_16x16x32_bf16 v[30:33], v[152:155], v[222:225], v[30:33]
	v_mfma_f32_16x16x32_bf16 v[26:29], v[162:165], v[222:225], v[26:29]
	v_mfma_f32_16x16x32_bf16 v[14:17], v[152:155], v[230:233], v[14:17]
	v_mfma_f32_16x16x32_bf16 v[10:13], v[162:165], v[230:233], v[10:13]
	v_mfma_f32_16x16x32_bf16 v[54:57], v[166:169], v[182:185], v[54:57]
	v_mfma_f32_16x16x32_bf16 v[50:53], v[174:177], v[182:185], v[50:53]
	v_mfma_f32_16x16x32_bf16 v[38:41], v[166:169], v[190:193], v[38:41]
	v_mfma_f32_16x16x32_bf16 v[34:37], v[174:177], v[190:193], v[34:37]
	v_mfma_f32_16x16x32_bf16 v[22:25], v[166:169], v[218:221], v[22:25]
	v_mfma_f32_16x16x32_bf16 v[18:21], v[174:177], v[218:221], v[18:21]
	v_mfma_f32_16x16x32_bf16 v[6:9], v[166:169], v[226:229], v[6:9]
	v_mfma_f32_16x16x32_bf16 v[2:5], v[174:177], v[226:229], v[2:5]
	v_mfma_f32_16x16x32_bf16 v[54:57], v[170:173], v[186:189], v[54:57]
	v_mfma_f32_16x16x32_bf16 v[50:53], v[178:181], v[186:189], v[50:53]
	v_mfma_f32_16x16x32_bf16 v[38:41], v[170:173], v[198:201], v[38:41]
	v_mfma_f32_16x16x32_bf16 v[34:37], v[178:181], v[198:201], v[34:37]
	v_mfma_f32_16x16x32_bf16 v[22:25], v[170:173], v[222:225], v[22:25]
	v_mfma_f32_16x16x32_bf16 v[18:21], v[178:181], v[222:225], v[18:21]
	v_mfma_f32_16x16x32_bf16 v[6:9], v[170:173], v[230:233], v[6:9]
	v_mfma_f32_16x16x32_bf16 v[2:5], v[178:181], v[230:233], v[2:5]
	s_setprio 0
	s_barrier
	s_add_i32 s96, 0, 0x18000
	v_add_u32_e32 v147, s96, v145
	s_add_i32 s97, 0, 0x1c000
	ds_read_b128 v[148:151], v147
	ds_read_b128 v[152:155], v147 offset:1024
	ds_read_b128 v[158:161], v147 offset:2048
	ds_read_b128 v[162:165], v147 offset:3072
	v_add_u32_e32 v147, s97, v145
	ds_read_b128 v[166:169], v147
	ds_read_b128 v[170:173], v147 offset:1024
	ds_read_b128 v[174:177], v147 offset:2048
	ds_read_b128 v[178:181], v147 offset:3072
	s_add_u32 s18, s18, 0x40000
	s_addc_u32 s19, s19, 0
	s_mov_b32 m0, s42
	v_lshl_add_u64 v[204:205], s[18:19], 0, v[130:131]
	ds_read_b128 v[182:185], v146 offset:32768
	ds_read_b128 v[186:189], v146 offset:33792
	ds_read_b128 v[190:193], v146 offset:34816
	ds_read_b128 v[198:201], v146 offset:35840
	ds_read_b128 v[218:221], v146 offset:36864
	ds_read_b128 v[222:225], v146 offset:37888
	ds_read_b128 v[226:229], v146 offset:38912
	ds_read_b128 v[230:233], v146 offset:39936
	global_load_lds_dwordx4 v[204:205], off
	v_lshl_add_u64 v[204:205], s[18:19], 0, v[134:135]
	s_mov_b32 m0, s43
	s_nop 0
	global_load_lds_dwordx4 v[204:205], off
	s_waitcnt vmcnt(8)
	s_waitcnt lgkmcnt(0)
	s_barrier
	s_setprio 1
	s_waitcnt lgkmcnt(0)
	v_mfma_f32_16x16x32_bf16 v[126:129], v[148:151], v[182:185], v[126:129]
	v_mfma_f32_16x16x32_bf16 v[122:125], v[158:161], v[182:185], v[122:125]
	v_mfma_f32_16x16x32_bf16 v[110:113], v[148:151], v[190:193], v[110:113]
	v_mfma_f32_16x16x32_bf16 v[106:109], v[158:161], v[190:193], v[106:109]
	v_mfma_f32_16x16x32_bf16 v[94:97], v[148:151], v[218:221], v[94:97]
	v_mfma_f32_16x16x32_bf16 v[90:93], v[158:161], v[218:221], v[90:93]
	v_mfma_f32_16x16x32_bf16 v[78:81], v[148:151], v[226:229], v[78:81]
	v_mfma_f32_16x16x32_bf16 v[74:77], v[158:161], v[226:229], v[74:77]
	v_mfma_f32_16x16x32_bf16 v[126:129], v[152:155], v[186:189], v[126:129]
	v_mfma_f32_16x16x32_bf16 v[122:125], v[162:165], v[186:189], v[122:125]
	v_mfma_f32_16x16x32_bf16 v[110:113], v[152:155], v[198:201], v[110:113]
	v_mfma_f32_16x16x32_bf16 v[106:109], v[162:165], v[198:201], v[106:109]
	v_mfma_f32_16x16x32_bf16 v[94:97], v[152:155], v[222:225], v[94:97]
	v_mfma_f32_16x16x32_bf16 v[90:93], v[162:165], v[222:225], v[90:93]
	v_mfma_f32_16x16x32_bf16 v[78:81], v[152:155], v[230:233], v[78:81]
	v_mfma_f32_16x16x32_bf16 v[74:77], v[162:165], v[230:233], v[74:77]
	v_mfma_f32_16x16x32_bf16 v[118:121], v[166:169], v[182:185], v[118:121]
	v_mfma_f32_16x16x32_bf16 v[114:117], v[174:177], v[182:185], v[114:117]
	v_mfma_f32_16x16x32_bf16 v[102:105], v[166:169], v[190:193], v[102:105]
	v_mfma_f32_16x16x32_bf16 v[98:101], v[174:177], v[190:193], v[98:101]
	v_mfma_f32_16x16x32_bf16 v[86:89], v[166:169], v[218:221], v[86:89]
	v_mfma_f32_16x16x32_bf16 v[82:85], v[174:177], v[218:221], v[82:85]
	v_mfma_f32_16x16x32_bf16 v[70:73], v[166:169], v[226:229], v[70:73]
	v_mfma_f32_16x16x32_bf16 v[66:69], v[174:177], v[226:229], v[66:69]
	v_mfma_f32_16x16x32_bf16 v[118:121], v[170:173], v[186:189], v[118:121]
	v_mfma_f32_16x16x32_bf16 v[114:117], v[178:181], v[186:189], v[114:117]
	v_mfma_f32_16x16x32_bf16 v[102:105], v[170:173], v[198:201], v[102:105]
	v_mfma_f32_16x16x32_bf16 v[98:101], v[178:181], v[198:201], v[98:101]
	v_mfma_f32_16x16x32_bf16 v[86:89], v[170:173], v[222:225], v[86:89]
	v_mfma_f32_16x16x32_bf16 v[82:85], v[178:181], v[222:225], v[82:85]
	v_mfma_f32_16x16x32_bf16 v[70:73], v[170:173], v[230:233], v[70:73]
	v_mfma_f32_16x16x32_bf16 v[66:69], v[178:181], v[230:233], v[66:69]
	s_setprio 0
	s_barrier
; #define PG8_STAGE(bufoff, gbase, voff) do { _Pragma("unroll") for (int _i = 0; _i < 2; ++_i) \
;         __builtin_amdgcn_global_load_lds((const unsigned*)((const char*)(gbase) + (voff)[_i]), (PG8_LAS unsigned*)(lds + (bufoff) + ldsw + _i * 8192), 16, 0, 0); } while (0)
; #define PG8_LDA(dst, b, h) do { _Pragma("unroll") for (int m = 0; m < 4; ++m) _Pragma("unroll") for (int k = 0; k < 2; ++k) dst[m][k] = *(const PG8_LAS bf16x8*)(lds + PG8_SA(b, h) + aoff + m * 2048 + k * 1024); } while (0)
; #define PG8_MMA(ai, bj, At, Bt) do { __builtin_amdgcn_s_setprio(1); _Pragma("unroll") for (int m = 0; m < 4; ++m) _Pragma("unroll") for (int n = 0; n < 2; ++n) _Pragma("unroll") for (int k = 0; k < 2; ++k) \
;         acc[ai][bj][m][n] = __builtin_amdgcn_mfma_f32_16x16x32_bf16(Bt[n][k], At[m][k], acc[ai][bj][m][n], 0, 0, 0); __builtin_amdgcn_s_setprio(0); } while (0)
; #define PG8_WAIT_V(n) asm volatile("s_waitcnt vmcnt(" #n ")" ::: "memory")
; #define PG8_WAIT_L(n) asm volatile("s_waitcnt lgkmcnt(" #n ")" ::: "memory")
; #define PG8_BAR __builtin_amdgcn_s_barrier()
; #define PG8_SCHED __builtin_amdgcn_sched_barrier(0)
; template <class Epi, class Sched, bool ALIGN_EPI = false, bool SP2 = false>
; __device__ __forceinline__ void gemm_phase(PG8_LAS unsigned char* lds, const Gemm g, const Sched& S, const Epi& E, int wv) {
;     ...
;         for (int t = 0; t < nt; t += 2) {
;             const bool last = (t == nt - 2);
;     ...
;             PG8_LDA(At, 1, 1); PG8_STAGE(PG8_SB(1, 0), b3, voffB); PG8_STAGE(PG8_SB(1, 1), b3 + hstepB, voffB); PG8_STAGE(PG8_SA(1, 0), a3, voffA);
;             PG8_WAIT_V(8); PG8_WAIT_L(0); PG8_BAR; PG8_MMA(1, 0, At, B0); PG8_MMA(1, 1, At, B1); PG8_BAR; PG8_SCHED;
	s_add_i32 s18, s96, s33
	v_lshl_add_u64 v[142:143], v[142:143], 0, s[20:21]
	s_mov_b32 m0, s18
	ds_read_b128 v[182:185], v146 offset:49152
	ds_read_b128 v[186:189], v146 offset:50176
	ds_read_b128 v[190:193], v146 offset:51200
	ds_read_b128 v[198:201], v146 offset:52224
	ds_read_b128 v[218:221], v146 offset:53248
	ds_read_b128 v[222:225], v146 offset:54272
	ds_read_b128 v[226:229], v146 offset:55296
	ds_read_b128 v[230:233], v146 offset:56320
	global_load_lds_dwordx4 v[142:143], off
	s_add_i32 m0, s18, 0x2000
	s_add_u32 s16, s16, 0x40080
	v_lshl_add_u64 v[142:143], v[194:195], 0, s[20:21]
	s_addc_u32 s17, s17, 0
	s_add_i32 s18, s97, s33
	global_load_lds_dwordx4 v[142:143], off
	v_lshl_add_u64 v[142:143], s[16:17], 0, v[132:133]
	s_mov_b32 m0, s18
	s_nop 0
	global_load_lds_dwordx4 v[142:143], off
	v_lshl_add_u64 v[142:143], s[16:17], 0, v[136:137]
	s_add_i32 m0, s18, 0x2000
	s_nop 0
	global_load_lds_dwordx4 v[142:143], off
	v_lshl_add_u64 v[142:143], v[196:197], 0, s[20:21]
	s_mov_b32 m0, s67
	s_nop 0
	global_load_lds_dwordx4 v[142:143], off
	v_lshl_add_u64 v[142:143], v[202:203], 0, s[20:21]
	s_mov_b32 m0, s69
	s_nop 0
	global_load_lds_dwordx4 v[142:143], off
	s_waitcnt vmcnt(8)
	s_waitcnt lgkmcnt(0)
	s_barrier
	s_setprio 1
	s_waitcnt lgkmcnt(0)
	v_mfma_f32_16x16x32_bf16 v[62:65], v[148:151], v[182:185], v[62:65]
	v_mfma_f32_16x16x32_bf16 v[58:61], v[158:161], v[182:185], v[58:61]
	v_mfma_f32_16x16x32_bf16 v[46:49], v[148:151], v[190:193], v[46:49]
	v_mfma_f32_16x16x32_bf16 v[42:45], v[158:161], v[190:193], v[42:45]
	v_mfma_f32_16x16x32_bf16 v[30:33], v[148:151], v[218:221], v[30:33]
	v_mfma_f32_16x16x32_bf16 v[26:29], v[158:161], v[218:221], v[26:29]
	v_mfma_f32_16x16x32_bf16 v[14:17], v[148:151], v[226:229], v[14:17]
	v_mfma_f32_16x16x32_bf16 v[10:13], v[158:161], v[226:229], v[10:13]
	v_mfma_f32_16x16x32_bf16 v[62:65], v[152:155], v[186:189], v[62:65]
	v_mfma_f32_16x16x32_bf16 v[58:61], v[162:165], v[186:189], v[58:61]
	v_mfma_f32_16x16x32_bf16 v[46:49], v[152:155], v[198:201], v[46:49]
	v_mfma_f32_16x16x32_bf16 v[42:45], v[162:165], v[198:201], v[42:45]
	v_mfma_f32_16x16x32_bf16 v[30:33], v[152:155], v[222:225], v[30:33]
	v_mfma_f32_16x16x32_bf16 v[26:29], v[162:165], v[222:225], v[26:29]
	v_mfma_f32_16x16x32_bf16 v[14:17], v[152:155], v[230:233], v[14:17]
	v_mfma_f32_16x16x32_bf16 v[10:13], v[162:165], v[230:233], v[10:13]
	v_mfma_f32_16x16x32_bf16 v[54:57], v[166:169], v[182:185], v[54:57]
	v_mfma_f32_16x16x32_bf16 v[50:53], v[174:177], v[182:185], v[50:53]
	v_mfma_f32_16x16x32_bf16 v[38:41], v[166:169], v[190:193], v[38:41]
	v_mfma_f32_16x16x32_bf16 v[34:37], v[174:177], v[190:193], v[34:37]
	v_mfma_f32_16x16x32_bf16 v[22:25], v[166:169], v[218:221], v[22:25]
	v_mfma_f32_16x16x32_bf16 v[18:21], v[174:177], v[218:221], v[18:21]
	v_mfma_f32_16x16x32_bf16 v[6:9], v[166:169], v[226:229], v[6:9]
	v_mfma_f32_16x16x32_bf16 v[2:5], v[174:177], v[226:229], v[2:5]
	v_mfma_f32_16x16x32_bf16 v[54:57], v[170:173], v[186:189], v[54:57]
	v_mfma_f32_16x16x32_bf16 v[50:53], v[178:181], v[186:189], v[50:53]
	v_mfma_f32_16x16x32_bf16 v[38:41], v[170:173], v[198:201], v[38:41]
	v_mfma_f32_16x16x32_bf16 v[34:37], v[178:181], v[198:201], v[34:37]
	v_mfma_f32_16x16x32_bf16 v[22:25], v[170:173], v[222:225], v[22:25]
	v_mfma_f32_16x16x32_bf16 v[18:21], v[178:181], v[222:225], v[18:21]
	v_mfma_f32_16x16x32_bf16 v[6:9], v[170:173], v[230:233], v[6:9]
	v_mfma_f32_16x16x32_bf16 v[2:5], v[178:181], v[230:233], v[2:5]
	s_setprio 0
	s_barrier
	s_add_i32 s79, s79, 2
	s_add_u32 s14, s14, 0x100
	s_addc_u32 s15, s15, 0
	s_add_u32 s76, s76, 0x100
	s_addc_u32 s77, s77, 0
	s_cmp_gt_u32 s79, 13
	s_cbranch_scc0 .LBB0_86
	s_and_b64 vcc, exec, s[2:3]
	s_cbranch_vccz .LBB0_89
	s_barrier

; #define PG8_STAGE(bufoff, gbase, voff) do { _Pragma("unroll") for (int _i = 0; _i < 2; ++_i) \
;         __builtin_amdgcn_global_load_lds((const unsigned*)((const char*)(gbase) + (voff)[_i]), (PG8_LAS unsigned*)(lds + (bufoff) + ldsw + _i * 8192), 16, 0, 0); } while (0)
; #define PG8_LDA(dst, b, h) do { _Pragma("unroll") for (int m = 0; m < 4; ++m) _Pragma("unroll") for (int k = 0; k < 2; ++k) dst[m][k] = *(const PG8_LAS bf16x8*)(lds + PG8_SA(b, h) + aoff + m * 2048 + k * 1024); } while (0)
; #define PG8_LDB(dst, b, h) do { _Pragma("unroll") for (int n = 0; n < 2; ++n) _Pragma("unroll") for (int k = 0; k < 2; ++k) dst[n][k] = *(const PG8_LAS bf16x8*)(lds + PG8_SB(b, h) + boff + n * 2048 + k * 1024); } while (0)
; #define PG8_MMA(ai, bj, At, Bt) do { __builtin_amdgcn_s_setprio(1); _Pragma("unroll") for (int m = 0; m < 4; ++m) _Pragma("unroll") for (int n = 0; n < 2; ++n) _Pragma("unroll") for (int k = 0; k < 2; ++k) \
;         acc[ai][bj][m][n] = __builtin_amdgcn_mfma_f32_16x16x32_bf16(Bt[n][k], At[m][k], acc[ai][bj][m][n], 0, 0, 0); __builtin_amdgcn_s_setprio(0); } while (0)
; #define PG8_WAIT_V(n) asm volatile("s_waitcnt vmcnt(" #n ")" ::: "memory")
; #define PG8_WAIT_L(n) asm volatile("s_waitcnt lgkmcnt(" #n ")" ::: "memory")
; #define PG8_BAR __builtin_amdgcn_s_barrier()
; #define PG8_SCHED __builtin_amdgcn_sched_barrier(0)
; template <class Epi, class Sched, bool ALIGN_EPI = false, bool SP2 = false>
; __device__ __forceinline__ void gemm_phase(PG8_LAS unsigned char* lds, const Gemm g, const Sched& S, const Epi& E, int wv) {
;     ...
;             const bool last = (t == nt - 2);
;             const char* a1 = cA + (size_t)(t + 1) * kstep;
;             const char* a2 = last ? nA : cA + (size_t)(t + 2) * kstep; const char* b2 = last ? nB : cB + (size_t)(t + 2) * kstep;
;             const char* a3 = a2 + kstep; const char* b3 = b2 + kstep;
;             if (last && has_next) S.a_ready(nxt);
;             if constexpr (SP2) {
;             PG8_LDB(B0, 0, 0); PG8_LDB(B1, 0, 1); PG8_SCHED; PG8_LDA(At, 0, 0); PG8_STAGE(PG8_SA(1, 1), a1 + hstepA, voffA);
;             PG8_WAIT_V(8); PG8_WAIT_L(0); PG8_BAR; PG8_MMA(0, 0, At, B0); PG8_MMA(0, 1, At, B1); PG8_BAR; PG8_SCHED;
;             PG8_LDA(At, 0, 1); PG8_STAGE(PG8_SB(0, 0), b2, voffB); PG8_STAGE(PG8_SB(0, 1), b2 + hstepB, voffB); PG8_STAGE(PG8_SA(0, 0), a2, voffA);
.LBB0_120:
	s_add_u32 s16, s14, 0xfffc0080
	s_addc_u32 s17, s15, -1
	s_add_i32 s96, 0, 0x10000
	s_cmp_eq_u32 s79, 12
	s_cselect_b32 s19, s7, s17
	s_cselect_b32 s18, s74, s16
	v_add_u32_e32 v142, s96, v145
	s_cselect_b32 s17, s5, s77
	s_cselect_b32 s16, s75, s76
	s_add_i32 vcc_lo, 0, 0x14000
	ds_read_b128 v[158:161], v142
	ds_read_b128 v[162:165], v142 offset:1024
	ds_read_b128 v[166:169], v142 offset:2048
	ds_read_b128 v[170:173], v142 offset:3072
	v_add_u32_e32 v142, vcc_lo, v145
	ds_read_b128 v[174:177], v142
	ds_read_b128 v[178:181], v142 offset:1024
	ds_read_b128 v[182:185], v142 offset:2048
	ds_read_b128 v[186:189], v142 offset:3072
	v_lshl_add_u64 v[142:143], s[14:15], 0, v[138:139]
	s_add_i32 m0, s40, 0xc000
	ds_read_b128 v[190:193], v153
	ds_read_b128 v[198:201], v153 offset:1024
	ds_read_b128 v[218:221], v153 offset:2048
	ds_read_b128 v[222:225], v153 offset:3072
	ds_read_b128 v[226:229], v153 offset:4096
	ds_read_b128 v[230:233], v153 offset:5120
	ds_read_b128 v[234:237], v153 offset:6144
	ds_read_b128 v[238:241], v153 offset:7168
	global_load_lds_dwordx4 v[142:143], off
	v_lshl_add_u64 v[142:143], s[14:15], 0, v[140:141]
	s_add_i32 m0, s40, 0xe000
	s_nop 0
	global_load_lds_dwordx4 v[142:143], off
	s_waitcnt vmcnt(8)
	s_waitcnt lgkmcnt(0)
	s_barrier
	s_setprio 1
	s_waitcnt lgkmcnt(0)
	v_mfma_f32_16x16x32_bf16 v[126:129], v[158:161], v[190:193], v[126:129]
	v_mfma_f32_16x16x32_bf16 v[122:125], v[166:169], v[190:193], v[122:125]
	v_mfma_f32_16x16x32_bf16 v[118:121], v[158:161], v[218:221], v[118:121]
	v_mfma_f32_16x16x32_bf16 v[110:113], v[166:169], v[218:221], v[110:113]
	v_mfma_f32_16x16x32_bf16 v[102:105], v[158:161], v[226:229], v[102:105]
	v_mfma_f32_16x16x32_bf16 v[94:97], v[166:169], v[226:229], v[94:97]
	v_mfma_f32_16x16x32_bf16 v[86:89], v[158:161], v[234:237], v[86:89]
	v_mfma_f32_16x16x32_bf16 v[78:81], v[166:169], v[234:237], v[78:81]
	v_mfma_f32_16x16x32_bf16 v[126:129], v[162:165], v[198:201], v[126:129]
	v_mfma_f32_16x16x32_bf16 v[122:125], v[170:173], v[198:201], v[122:125]
	v_mfma_f32_16x16x32_bf16 v[118:121], v[162:165], v[222:225], v[118:121]
	v_mfma_f32_16x16x32_bf16 v[110:113], v[170:173], v[222:225], v[110:113]
	v_mfma_f32_16x16x32_bf16 v[102:105], v[162:165], v[230:233], v[102:105]
	v_mfma_f32_16x16x32_bf16 v[94:97], v[170:173], v[230:233], v[94:97]
	v_mfma_f32_16x16x32_bf16 v[86:89], v[162:165], v[238:241], v[86:89]
	v_mfma_f32_16x16x32_bf16 v[78:81], v[170:173], v[238:241], v[78:81]
	v_mfma_f32_16x16x32_bf16 v[114:117], v[174:177], v[190:193], v[114:117]
	v_mfma_f32_16x16x32_bf16 v[106:109], v[182:185], v[190:193], v[106:109]
	v_mfma_f32_16x16x32_bf16 v[98:101], v[174:177], v[218:221], v[98:101]
	v_mfma_f32_16x16x32_bf16 v[90:93], v[182:185], v[218:221], v[90:93]
	v_mfma_f32_16x16x32_bf16 v[82:85], v[174:177], v[226:229], v[82:85]
	v_mfma_f32_16x16x32_bf16 v[74:77], v[182:185], v[226:229], v[74:77]
	v_mfma_f32_16x16x32_bf16 v[70:73], v[174:177], v[234:237], v[70:73]
	v_mfma_f32_16x16x32_bf16 v[66:69], v[182:185], v[234:237], v[66:69]
	v_mfma_f32_16x16x32_bf16 v[114:117], v[178:181], v[198:201], v[114:117]
	v_mfma_f32_16x16x32_bf16 v[106:109], v[186:189], v[198:201], v[106:109]
	v_mfma_f32_16x16x32_bf16 v[98:101], v[178:181], v[222:225], v[98:101]
	v_mfma_f32_16x16x32_bf16 v[90:93], v[186:189], v[222:225], v[90:93]
	v_mfma_f32_16x16x32_bf16 v[82:85], v[178:181], v[230:233], v[82:85]
	v_mfma_f32_16x16x32_bf16 v[74:77], v[186:189], v[230:233], v[74:77]
	v_mfma_f32_16x16x32_bf16 v[70:73], v[178:181], v[238:241], v[70:73]
	v_mfma_f32_16x16x32_bf16 v[66:69], v[186:189], v[238:241], v[66:69]
	s_setprio 0
	s_barrier
	s_add_i32 s96, s96, s33
	v_lshl_add_u64 v[142:143], s[16:17], 0, v[132:133]
	s_mov_b32 m0, s96
	ds_read_b128 v[190:193], v153 offset:16384
	ds_read_b128 v[198:201], v153 offset:17408
	ds_read_b128 v[218:221], v153 offset:18432
	ds_read_b128 v[222:225], v153 offset:19456
	ds_read_b128 v[226:229], v153 offset:20480
	ds_read_b128 v[230:233], v153 offset:21504
	ds_read_b128 v[234:237], v153 offset:22528
	ds_read_b128 v[238:241], v153 offset:23552
	global_load_lds_dwordx4 v[142:143], off
	s_add_i32 m0, s96, 0x2000
	s_add_u32 s96, s16, 0x40000
	v_lshl_add_u64 v[154:155], s[16:17], 0, v[136:137]
	s_addc_u32 s97, s17, 0
	s_add_i32 vcc_lo, vcc_lo, s33
	global_load_lds_dwordx4 v[154:155], off
	v_lshl_add_u64 v[194:195], s[96:97], 0, v[132:133]
	s_mov_b32 m0, vcc_lo
	v_lshl_add_u64 v[196:197], s[18:19], 0, v[134:135]
	global_load_lds_dwordx4 v[194:195], off
	v_lshl_add_u64 v[194:195], s[96:97], 0, v[136:137]
	s_add_i32 m0, vcc_lo, 0x2000
	s_nop 0
	global_load_lds_dwordx4 v[194:195], off
	v_lshl_add_u64 v[194:195], s[18:19], 0, v[130:131]
	s_mov_b32 m0, s40
	s_nop 0
	global_load_lds_dwordx4 v[194:195], off
	s_mov_b32 m0, s41
	s_nop 0
	global_load_lds_dwordx4 v[196:197], off
	s_waitcnt vmcnt(8)
	s_waitcnt lgkmcnt(0)
	s_barrier
; #define PG8_STAGE(bufoff, gbase, voff) do { _Pragma("unroll") for (int _i = 0; _i < 2; ++_i) \
;         __builtin_amdgcn_global_load_lds((const unsigned*)((const char*)(gbase) + (voff)[_i]), (PG8_LAS unsigned*)(lds + (bufoff) + ldsw + _i * 8192), 16, 0, 0); } while (0)
; #define PG8_LDA(dst, b, h) do { _Pragma("unroll") for (int m = 0; m < 4; ++m) _Pragma("unroll") for (int k = 0; k < 2; ++k) dst[m][k] = *(const PG8_LAS bf16x8*)(lds + PG8_SA(b, h) + aoff + m * 2048 + k * 1024); } while (0)
; #define PG8_LDB(dst, b, h) do { _Pragma("unroll") for (int n = 0; n < 2; ++n) _Pragma("unroll") for (int k = 0; k < 2; ++k) dst[n][k] = *(const PG8_LAS bf16x8*)(lds + PG8_SB(b, h) + boff + n * 2048 + k * 1024); } while (0)
; #define PG8_MMA(ai, bj, At, Bt) do { __builtin_amdgcn_s_setprio(1); _Pragma("unroll") for (int m = 0; m < 4; ++m) _Pragma("unroll") for (int n = 0; n < 2; ++n) _Pragma("unroll") for (int k = 0; k < 2; ++k) \
;         acc[ai][bj][m][n] = __builtin_amdgcn_mfma_f32_16x16x32_bf16(Bt[n][k], At[m][k], acc[ai][bj][m][n], 0, 0, 0); __builtin_amdgcn_s_setprio(0); } while (0)
; #define PG8_WAIT_V(n) asm volatile("s_waitcnt vmcnt(" #n ")" ::: "memory")
; #define PG8_WAIT_L(n) asm volatile("s_waitcnt lgkmcnt(" #n ")" ::: "memory")
; #define PG8_BAR __builtin_amdgcn_s_barrier()
; #define PG8_SCHED __builtin_amdgcn_sched_barrier(0)
; template <class Epi, class Sched, bool ALIGN_EPI = false, bool SP2 = false>
; __device__ __forceinline__ void gemm_phase(PG8_LAS unsigned char* lds, const Gemm g, const Sched& S, const Epi& E, int wv) {
;     ...
;             PG8_WAIT_V(8); PG8_WAIT_L(0); PG8_BAR; PG8_MMA(1, 0, At, B0); PG8_MMA(1, 1, At, B1); PG8_BAR; PG8_SCHED;
;             PG8_LDB(B0, 1, 0); PG8_LDB(B1, 1, 1); PG8_SCHED; PG8_LDA(At, 1, 0); PG8_STAGE(PG8_SA(0, 1), a2 + hstepA, voffA);
;             PG8_WAIT_V(8); PG8_WAIT_L(0); PG8_BAR; PG8_MMA(0, 0, At, B0); PG8_MMA(0, 1, At, B1); PG8_BAR; PG8_SCHED;
	s_setprio 1
	s_waitcnt lgkmcnt(0)
	v_mfma_f32_16x16x32_bf16 v[62:65], v[158:161], v[190:193], v[62:65]
	v_mfma_f32_16x16x32_bf16 v[58:61], v[166:169], v[190:193], v[58:61]
	v_mfma_f32_16x16x32_bf16 v[54:57], v[158:161], v[218:221], v[54:57]
	v_mfma_f32_16x16x32_bf16 v[46:49], v[166:169], v[218:221], v[46:49]
	v_mfma_f32_16x16x32_bf16 v[38:41], v[158:161], v[226:229], v[38:41]
	v_mfma_f32_16x16x32_bf16 v[30:33], v[166:169], v[226:229], v[30:33]
	v_mfma_f32_16x16x32_bf16 v[22:25], v[158:161], v[234:237], v[22:25]
	v_mfma_f32_16x16x32_bf16 v[14:17], v[166:169], v[234:237], v[14:17]
	v_mfma_f32_16x16x32_bf16 v[62:65], v[162:165], v[198:201], v[62:65]
	v_mfma_f32_16x16x32_bf16 v[58:61], v[170:173], v[198:201], v[58:61]
	v_mfma_f32_16x16x32_bf16 v[54:57], v[162:165], v[222:225], v[54:57]
	v_mfma_f32_16x16x32_bf16 v[46:49], v[170:173], v[222:225], v[46:49]
	v_mfma_f32_16x16x32_bf16 v[38:41], v[162:165], v[230:233], v[38:41]
	v_mfma_f32_16x16x32_bf16 v[30:33], v[170:173], v[230:233], v[30:33]
	v_mfma_f32_16x16x32_bf16 v[22:25], v[162:165], v[238:241], v[22:25]
	v_mfma_f32_16x16x32_bf16 v[14:17], v[170:173], v[238:241], v[14:17]
	v_mfma_f32_16x16x32_bf16 v[50:53], v[174:177], v[190:193], v[50:53]
	v_mfma_f32_16x16x32_bf16 v[42:45], v[182:185], v[190:193], v[42:45]
	v_mfma_f32_16x16x32_bf16 v[34:37], v[174:177], v[218:221], v[34:37]
	v_mfma_f32_16x16x32_bf16 v[26:29], v[182:185], v[218:221], v[26:29]
	v_mfma_f32_16x16x32_bf16 v[18:21], v[174:177], v[226:229], v[18:21]
	v_mfma_f32_16x16x32_bf16 v[10:13], v[182:185], v[226:229], v[10:13]
	v_mfma_f32_16x16x32_bf16 v[6:9], v[174:177], v[234:237], v[6:9]
	v_mfma_f32_16x16x32_bf16 v[2:5], v[182:185], v[234:237], v[2:5]
	v_mfma_f32_16x16x32_bf16 v[50:53], v[178:181], v[198:201], v[50:53]
	v_mfma_f32_16x16x32_bf16 v[42:45], v[186:189], v[198:201], v[42:45]
	v_mfma_f32_16x16x32_bf16 v[34:37], v[178:181], v[222:225], v[34:37]
	v_mfma_f32_16x16x32_bf16 v[26:29], v[186:189], v[222:225], v[26:29]
	v_mfma_f32_16x16x32_bf16 v[18:21], v[178:181], v[230:233], v[18:21]
	v_mfma_f32_16x16x32_bf16 v[10:13], v[186:189], v[230:233], v[10:13]
	v_mfma_f32_16x16x32_bf16 v[6:9], v[178:181], v[238:241], v[6:9]
	v_mfma_f32_16x16x32_bf16 v[2:5], v[186:189], v[238:241], v[2:5]
	s_setprio 0
	s_barrier
	s_add_i32 s96, 0, 0x18000
	v_add_u32_e32 v157, s96, v145
	s_add_i32 s97, 0, 0x1c000
	ds_read_b128 v[158:161], v157
	ds_read_b128 v[162:165], v157 offset:1024
	ds_read_b128 v[166:169], v157 offset:2048
	ds_read_b128 v[170:173], v157 offset:3072
	v_add_u32_e32 v157, s97, v145
	ds_read_b128 v[174:177], v157
	ds_read_b128 v[178:181], v157 offset:1024
	ds_read_b128 v[182:185], v157 offset:2048
	ds_read_b128 v[186:189], v157 offset:3072
	s_add_u32 s18, s18, 0x40000
	s_addc_u32 s19, s19, 0
	s_mov_b32 m0, s42
	v_lshl_add_u64 v[202:203], s[18:19], 0, v[130:131]
	ds_read_b128 v[190:193], v153 offset:32768
	ds_read_b128 v[198:201], v153 offset:33792
	ds_read_b128 v[218:221], v153 offset:34816
	ds_read_b128 v[222:225], v153 offset:35840
	ds_read_b128 v[226:229], v153 offset:36864
	ds_read_b128 v[230:233], v153 offset:37888
	ds_read_b128 v[234:237], v153 offset:38912
	ds_read_b128 v[238:241], v153 offset:39936
	global_load_lds_dwordx4 v[202:203], off
	v_lshl_add_u64 v[202:203], s[18:19], 0, v[134:135]
	s_mov_b32 m0, s43
	s_nop 0
	global_load_lds_dwordx4 v[202:203], off
	s_waitcnt vmcnt(8)
	s_waitcnt lgkmcnt(0)
	s_barrier
	s_setprio 1
	s_waitcnt lgkmcnt(0)
	v_mfma_f32_16x16x32_bf16 v[126:129], v[158:161], v[190:193], v[126:129]
	v_mfma_f32_16x16x32_bf16 v[122:125], v[166:169], v[190:193], v[122:125]
	v_mfma_f32_16x16x32_bf16 v[118:121], v[158:161], v[218:221], v[118:121]
	v_mfma_f32_16x16x32_bf16 v[110:113], v[166:169], v[218:221], v[110:113]
	v_mfma_f32_16x16x32_bf16 v[102:105], v[158:161], v[226:229], v[102:105]
	v_mfma_f32_16x16x32_bf16 v[94:97], v[166:169], v[226:229], v[94:97]
	v_mfma_f32_16x16x32_bf16 v[86:89], v[158:161], v[234:237], v[86:89]
	v_mfma_f32_16x16x32_bf16 v[78:81], v[166:169], v[234:237], v[78:81]
	v_mfma_f32_16x16x32_bf16 v[126:129], v[162:165], v[198:201], v[126:129]
	v_mfma_f32_16x16x32_bf16 v[122:125], v[170:173], v[198:201], v[122:125]
	v_mfma_f32_16x16x32_bf16 v[118:121], v[162:165], v[222:225], v[118:121]
	v_mfma_f32_16x16x32_bf16 v[110:113], v[170:173], v[222:225], v[110:113]
	v_mfma_f32_16x16x32_bf16 v[102:105], v[162:165], v[230:233], v[102:105]
	v_mfma_f32_16x16x32_bf16 v[94:97], v[170:173], v[230:233], v[94:97]
	v_mfma_f32_16x16x32_bf16 v[86:89], v[162:165], v[238:241], v[86:89]
	v_mfma_f32_16x16x32_bf16 v[78:81], v[170:173], v[238:241], v[78:81]
	v_mfma_f32_16x16x32_bf16 v[114:117], v[174:177], v[190:193], v[114:117]
	v_mfma_f32_16x16x32_bf16 v[106:109], v[182:185], v[190:193], v[106:109]
	v_mfma_f32_16x16x32_bf16 v[98:101], v[174:177], v[218:221], v[98:101]
	v_mfma_f32_16x16x32_bf16 v[90:93], v[182:185], v[218:221], v[90:93]
	v_mfma_f32_16x16x32_bf16 v[82:85], v[174:177], v[226:229], v[82:85]
	v_mfma_f32_16x16x32_bf16 v[74:77], v[182:185], v[226:229], v[74:77]
	v_mfma_f32_16x16x32_bf16 v[70:73], v[174:177], v[234:237], v[70:73]
	v_mfma_f32_16x16x32_bf16 v[66:69], v[182:185], v[234:237], v[66:69]
	v_mfma_f32_16x16x32_bf16 v[114:117], v[178:181], v[198:201], v[114:117]
	v_mfma_f32_16x16x32_bf16 v[106:109], v[186:189], v[198:201], v[106:109]
	v_mfma_f32_16x16x32_bf16 v[98:101], v[178:181], v[222:225], v[98:101]
	v_mfma_f32_16x16x32_bf16 v[90:93], v[186:189], v[222:225], v[90:93]
	v_mfma_f32_16x16x32_bf16 v[82:85], v[178:181], v[230:233], v[82:85]
	v_mfma_f32_16x16x32_bf16 v[74:77], v[186:189], v[230:233], v[74:77]
	v_mfma_f32_16x16x32_bf16 v[70:73], v[178:181], v[238:241], v[70:73]
	v_mfma_f32_16x16x32_bf16 v[66:69], v[186:189], v[238:241], v[66:69]
	s_setprio 0
	s_barrier
; #define PG8_STAGE(bufoff, gbase, voff) do { _Pragma("unroll") for (int _i = 0; _i < 2; ++_i) \
;         __builtin_amdgcn_global_load_lds((const unsigned*)((const char*)(gbase) + (voff)[_i]), (PG8_LAS unsigned*)(lds + (bufoff) + ldsw + _i * 8192), 16, 0, 0); } while (0)
; #define PG8_LDA(dst, b, h) do { _Pragma("unroll") for (int m = 0; m < 4; ++m) _Pragma("unroll") for (int k = 0; k < 2; ++k) dst[m][k] = *(const PG8_LAS bf16x8*)(lds + PG8_SA(b, h) + aoff + m * 2048 + k * 1024); } while (0)
; #define PG8_MMA(ai, bj, At, Bt) do { __builtin_amdgcn_s_setprio(1); _Pragma("unroll") for (int m = 0; m < 4; ++m) _Pragma("unroll") for (int n = 0; n < 2; ++n) _Pragma("unroll") for (int k = 0; k < 2; ++k) \
;         acc[ai][bj][m][n] = __builtin_amdgcn_mfma_f32_16x16x32_bf16(Bt[n][k], At[m][k], acc[ai][bj][m][n], 0, 0, 0); __builtin_amdgcn_s_setprio(0); } while (0)
; #define PG8_WAIT_V(n) asm volatile("s_waitcnt vmcnt(" #n ")" ::: "memory")
; #define PG8_WAIT_L(n) asm volatile("s_waitcnt lgkmcnt(" #n ")" ::: "memory")
; #define PG8_BAR __builtin_amdgcn_s_barrier()
; #define PG8_SCHED __builtin_amdgcn_sched_barrier(0)
; template <class Epi, class Sched, bool ALIGN_EPI = false, bool SP2 = false>
; __device__ __forceinline__ void gemm_phase(PG8_LAS unsigned char* lds, const Gemm g, const Sched& S, const Epi& E, int wv) {
;     ...
;         for (int t = 0; t < nt; t += 2) {
;             const bool last = (t == nt - 2);
;     ...
;             PG8_LDA(At, 1, 1); PG8_STAGE(PG8_SB(1, 0), b3, voffB); PG8_STAGE(PG8_SB(1, 1), b3 + hstepB, voffB); PG8_STAGE(PG8_SA(1, 0), a3, voffA);
;             PG8_WAIT_V(8); PG8_WAIT_L(0); PG8_BAR; PG8_MMA(1, 0, At, B0); PG8_MMA(1, 1, At, B1); PG8_BAR; PG8_SCHED;
	s_add_i32 s18, s96, s33
	v_lshl_add_u64 v[142:143], v[142:143], 0, s[20:21]
	s_mov_b32 m0, s18
	ds_read_b128 v[190:193], v153 offset:49152
	ds_read_b128 v[198:201], v153 offset:50176
	ds_read_b128 v[218:221], v153 offset:51200
	ds_read_b128 v[222:225], v153 offset:52224
	ds_read_b128 v[226:229], v153 offset:53248
	ds_read_b128 v[230:233], v153 offset:54272
	ds_read_b128 v[234:237], v153 offset:55296
	ds_read_b128 v[238:241], v153 offset:56320
	global_load_lds_dwordx4 v[142:143], off
	s_add_i32 m0, s18, 0x2000
	s_add_u32 s16, s16, 0x40080
	v_lshl_add_u64 v[142:143], v[154:155], 0, s[20:21]
	s_addc_u32 s17, s17, 0
	s_add_i32 s18, s97, s33
	global_load_lds_dwordx4 v[142:143], off
	v_lshl_add_u64 v[142:143], s[16:17], 0, v[132:133]
	s_mov_b32 m0, s18
	s_nop 0
	global_load_lds_dwordx4 v[142:143], off
	v_lshl_add_u64 v[142:143], s[16:17], 0, v[136:137]
	s_add_i32 m0, s18, 0x2000
	s_nop 0
	global_load_lds_dwordx4 v[142:143], off
	v_lshl_add_u64 v[142:143], v[194:195], 0, s[20:21]
	s_mov_b32 m0, s67
	s_nop 0
	global_load_lds_dwordx4 v[142:143], off
	v_lshl_add_u64 v[142:143], v[196:197], 0, s[20:21]
	s_mov_b32 m0, s69
	s_nop 0
	global_load_lds_dwordx4 v[142:143], off
	s_waitcnt vmcnt(8)
	s_waitcnt lgkmcnt(0)
	s_barrier
	s_setprio 1
	s_waitcnt lgkmcnt(0)
	v_mfma_f32_16x16x32_bf16 v[62:65], v[158:161], v[190:193], v[62:65]
	v_mfma_f32_16x16x32_bf16 v[58:61], v[166:169], v[190:193], v[58:61]
	v_mfma_f32_16x16x32_bf16 v[54:57], v[158:161], v[218:221], v[54:57]
	v_mfma_f32_16x16x32_bf16 v[46:49], v[166:169], v[218:221], v[46:49]
	v_mfma_f32_16x16x32_bf16 v[38:41], v[158:161], v[226:229], v[38:41]
	v_mfma_f32_16x16x32_bf16 v[30:33], v[166:169], v[226:229], v[30:33]
	v_mfma_f32_16x16x32_bf16 v[22:25], v[158:161], v[234:237], v[22:25]
	v_mfma_f32_16x16x32_bf16 v[14:17], v[166:169], v[234:237], v[14:17]
	v_mfma_f32_16x16x32_bf16 v[62:65], v[162:165], v[198:201], v[62:65]
	v_mfma_f32_16x16x32_bf16 v[58:61], v[170:173], v[198:201], v[58:61]
	v_mfma_f32_16x16x32_bf16 v[54:57], v[162:165], v[222:225], v[54:57]
	v_mfma_f32_16x16x32_bf16 v[46:49], v[170:173], v[222:225], v[46:49]
	v_mfma_f32_16x16x32_bf16 v[38:41], v[162:165], v[230:233], v[38:41]
	v_mfma_f32_16x16x32_bf16 v[30:33], v[170:173], v[230:233], v[30:33]
	v_mfma_f32_16x16x32_bf16 v[22:25], v[162:165], v[238:241], v[22:25]
	v_mfma_f32_16x16x32_bf16 v[14:17], v[170:173], v[238:241], v[14:17]
	v_mfma_f32_16x16x32_bf16 v[50:53], v[174:177], v[190:193], v[50:53]
	v_mfma_f32_16x16x32_bf16 v[42:45], v[182:185], v[190:193], v[42:45]
	v_mfma_f32_16x16x32_bf16 v[34:37], v[174:177], v[218:221], v[34:37]
	v_mfma_f32_16x16x32_bf16 v[26:29], v[182:185], v[218:221], v[26:29]
	v_mfma_f32_16x16x32_bf16 v[18:21], v[174:177], v[226:229], v[18:21]
	v_mfma_f32_16x16x32_bf16 v[10:13], v[182:185], v[226:229], v[10:13]
	v_mfma_f32_16x16x32_bf16 v[6:9], v[174:177], v[234:237], v[6:9]
	v_mfma_f32_16x16x32_bf16 v[2:5], v[182:185], v[234:237], v[2:5]
	v_mfma_f32_16x16x32_bf16 v[50:53], v[178:181], v[198:201], v[50:53]
	v_mfma_f32_16x16x32_bf16 v[42:45], v[186:189], v[198:201], v[42:45]
	v_mfma_f32_16x16x32_bf16 v[34:37], v[178:181], v[222:225], v[34:37]
	v_mfma_f32_16x16x32_bf16 v[26:29], v[186:189], v[222:225], v[26:29]
	v_mfma_f32_16x16x32_bf16 v[18:21], v[178:181], v[230:233], v[18:21]
	v_mfma_f32_16x16x32_bf16 v[10:13], v[186:189], v[230:233], v[10:13]
	v_mfma_f32_16x16x32_bf16 v[6:9], v[178:181], v[238:241], v[6:9]
	v_mfma_f32_16x16x32_bf16 v[2:5], v[186:189], v[238:241], v[2:5]
	s_setprio 0
	s_barrier
	s_add_i32 s79, s79, 2
	s_add_u32 s14, s14, 0x100
	s_addc_u32 s15, s15, 0
	s_add_u32 s76, s76, 0x100
	s_addc_u32 s77, s77, 0
	s_cmp_gt_u32 s79, 13
	s_cbranch_scc0 .LBB0_120
	s_and_b64 vcc, exec, s[2:3]
	s_cbranch_vccz .LBB0_123
	s_barrier

; #define PG8_STAGE(bufoff, gbase, voff) do { _Pragma("unroll") for (int _i = 0; _i < 2; ++_i) \
;         __builtin_amdgcn_global_load_lds((const unsigned*)((const char*)(gbase) + (voff)[_i]), (PG8_LAS unsigned*)(lds + (bufoff) + ldsw + _i * 8192), 16, 0, 0); } while (0)
; #define PG8_LDA(dst, b, h) do { _Pragma("unroll") for (int m = 0; m < 4; ++m) _Pragma("unroll") for (int k = 0; k < 2; ++k) dst[m][k] = *(const PG8_LAS bf16x8*)(lds + PG8_SA(b, h) + aoff + m * 2048 + k * 1024); } while (0)
; #define PG8_LDB(dst, b, h) do { _Pragma("unroll") for (int n = 0; n < 2; ++n) _Pragma("unroll") for (int k = 0; k < 2; ++k) dst[n][k] = *(const PG8_LAS bf16x8*)(lds + PG8_SB(b, h) + boff + n * 2048 + k * 1024); } while (0)
; #define PG8_MMA(ai, bj, At, Bt) do { __builtin_amdgcn_s_setprio(1); _Pragma("unroll") for (int m = 0; m < 4; ++m) _Pragma("unroll") for (int n = 0; n < 2; ++n) _Pragma("unroll") for (int k = 0; k < 2; ++k) \
;         acc[ai][bj][m][n] = __builtin_amdgcn_mfma_f32_16x16x32_bf16(Bt[n][k], At[m][k], acc[ai][bj][m][n], 0, 0, 0); __builtin_amdgcn_s_setprio(0); } while (0)
; #define PG8_WAIT_V(n) asm volatile("s_waitcnt vmcnt(" #n ")" ::: "memory")
; #define PG8_WAIT_L(n) asm volatile("s_waitcnt lgkmcnt(" #n ")" ::: "memory")
; #define PG8_BAR __builtin_amdgcn_s_barrier()
; #define PG8_SCHED __builtin_amdgcn_sched_barrier(0)
; template <class Epi, class Sched, bool ALIGN_EPI = false, bool SP2 = false>
; __device__ __forceinline__ void gemm_phase(PG8_LAS unsigned char* lds, const Gemm g, const Sched& S, const Epi& E, int wv) {
;     ...
;             const bool last = (t == nt - 2);
;             const char* a1 = cA + (size_t)(t + 1) * kstep;
;             const char* a2 = last ? nA : cA + (size_t)(t + 2) * kstep; const char* b2 = last ? nB : cB + (size_t)(t + 2) * kstep;
;             const char* a3 = a2 + kstep; const char* b3 = b2 + kstep;
;             if (last && has_next) S.a_ready(nxt);
;             if constexpr (SP2) {
;             PG8_LDB(B0, 0, 0); PG8_LDB(B1, 0, 1); PG8_SCHED; PG8_LDA(At, 0, 0); PG8_STAGE(PG8_SA(1, 1), a1 + hstepA, voffA);
;             PG8_WAIT_V(8); PG8_WAIT_L(0); PG8_BAR; PG8_MMA(0, 0, At, B0); PG8_MMA(0, 1, At, B1); PG8_BAR; PG8_SCHED;
;             PG8_LDA(At, 0, 1); PG8_STAGE(PG8_SB(0, 0), b2, voffB); PG8_STAGE(PG8_SB(0, 1), b2 + hstepB, voffB); PG8_STAGE(PG8_SA(0, 0), a2, voffA);
.LBB0_140:
	s_add_u32 s6, s4, 0x100
	s_addc_u32 s7, s5, 0
	s_add_i32 s65, 0, 0x10000
	s_cmp_eq_u32 s37, 12
	s_cselect_b32 s11, s41, s7
	s_cselect_b32 s10, s40, s6
	v_add_u32_e32 v0, s65, v146
	s_cselect_b32 s9, s30, s36
	s_cselect_b32 s8, s31, s33
	s_add_i32 s69, 0, 0x14000
	ds_read_b128 v[142:145], v0
	ds_read_b128 v[166:169], v0 offset:1024
	ds_read_b128 v[170:173], v0 offset:2048
	ds_read_b128 v[174:177], v0 offset:3072
	v_add_u32_e32 v0, s69, v146
	ds_read_b128 v[178:181], v0
	ds_read_b128 v[182:185], v0 offset:1024
	ds_read_b128 v[186:189], v0 offset:2048
	ds_read_b128 v[190:193], v0 offset:3072
	v_lshl_add_u64 v[194:195], s[4:5], 0, v[138:139]
	s_add_i32 m0, s1, 0xc000
	ds_read_b128 v[198:201], v165
	ds_read_b128 v[218:221], v165 offset:1024
	ds_read_b128 v[222:225], v165 offset:2048
	ds_read_b128 v[226:229], v165 offset:3072
	ds_read_b128 v[230:233], v165 offset:4096
	ds_read_b128 v[234:237], v165 offset:5120
	ds_read_b128 v[238:241], v165 offset:6144
	ds_read_b128 v[242:245], v165 offset:7168
	global_load_lds_dwordx4 v[194:195], off
	v_lshl_add_u64 v[194:195], s[4:5], 0, v[140:141]
	s_add_i32 m0, s1, 0xe000
	s_nop 0
	global_load_lds_dwordx4 v[194:195], off
	s_waitcnt vmcnt(8)
	s_waitcnt lgkmcnt(0)
	s_barrier
	s_setprio 1
	s_waitcnt lgkmcnt(0)
	v_mfma_f32_16x16x32_bf16 v[126:129], v[142:145], v[198:201], v[126:129]
	v_mfma_f32_16x16x32_bf16 v[122:125], v[170:173], v[198:201], v[122:125]
	v_mfma_f32_16x16x32_bf16 v[110:113], v[142:145], v[222:225], v[110:113]
	v_mfma_f32_16x16x32_bf16 v[106:109], v[170:173], v[222:225], v[106:109]
	v_mfma_f32_16x16x32_bf16 v[94:97], v[142:145], v[230:233], v[94:97]
	v_mfma_f32_16x16x32_bf16 v[90:93], v[170:173], v[230:233], v[90:93]
	v_mfma_f32_16x16x32_bf16 v[78:81], v[142:145], v[238:241], v[78:81]
	v_mfma_f32_16x16x32_bf16 v[74:77], v[170:173], v[238:241], v[74:77]
	v_mfma_f32_16x16x32_bf16 v[126:129], v[166:169], v[218:221], v[126:129]
	v_mfma_f32_16x16x32_bf16 v[122:125], v[174:177], v[218:221], v[122:125]
	v_mfma_f32_16x16x32_bf16 v[110:113], v[166:169], v[226:229], v[110:113]
	v_mfma_f32_16x16x32_bf16 v[106:109], v[174:177], v[226:229], v[106:109]
	v_mfma_f32_16x16x32_bf16 v[94:97], v[166:169], v[234:237], v[94:97]
	v_mfma_f32_16x16x32_bf16 v[90:93], v[174:177], v[234:237], v[90:93]
	v_mfma_f32_16x16x32_bf16 v[78:81], v[166:169], v[242:245], v[78:81]
	v_mfma_f32_16x16x32_bf16 v[74:77], v[174:177], v[242:245], v[74:77]
	v_mfma_f32_16x16x32_bf16 v[118:121], v[178:181], v[198:201], v[118:121]
	v_mfma_f32_16x16x32_bf16 v[114:117], v[186:189], v[198:201], v[114:117]
	v_mfma_f32_16x16x32_bf16 v[102:105], v[178:181], v[222:225], v[102:105]
	v_mfma_f32_16x16x32_bf16 v[98:101], v[186:189], v[222:225], v[98:101]
	v_mfma_f32_16x16x32_bf16 v[86:89], v[178:181], v[230:233], v[86:89]
	v_mfma_f32_16x16x32_bf16 v[82:85], v[186:189], v[230:233], v[82:85]
	v_mfma_f32_16x16x32_bf16 v[70:73], v[178:181], v[238:241], v[70:73]
	v_mfma_f32_16x16x32_bf16 v[66:69], v[186:189], v[238:241], v[66:69]
	v_mfma_f32_16x16x32_bf16 v[118:121], v[182:185], v[218:221], v[118:121]
	v_mfma_f32_16x16x32_bf16 v[114:117], v[190:193], v[218:221], v[114:117]
	v_mfma_f32_16x16x32_bf16 v[102:105], v[182:185], v[226:229], v[102:105]
	v_mfma_f32_16x16x32_bf16 v[98:101], v[190:193], v[226:229], v[98:101]
	v_mfma_f32_16x16x32_bf16 v[86:89], v[182:185], v[234:237], v[86:89]
	v_mfma_f32_16x16x32_bf16 v[82:85], v[190:193], v[234:237], v[82:85]
	v_mfma_f32_16x16x32_bf16 v[70:73], v[182:185], v[242:245], v[70:73]
	v_mfma_f32_16x16x32_bf16 v[66:69], v[190:193], v[242:245], v[66:69]
	s_setprio 0
	s_barrier
	s_add_i32 s4, s65, s14
	v_lshl_add_u64 v[194:195], s[8:9], 0, v[132:133]
	s_mov_b32 m0, s4
	ds_read_b128 v[198:201], v165 offset:16384
	ds_read_b128 v[218:221], v165 offset:17408
	ds_read_b128 v[222:225], v165 offset:18432
	ds_read_b128 v[226:229], v165 offset:19456
	ds_read_b128 v[230:233], v165 offset:20480
	ds_read_b128 v[234:237], v165 offset:21504
	ds_read_b128 v[238:241], v165 offset:22528
	ds_read_b128 v[242:245], v165 offset:23552
	global_load_lds_dwordx4 v[194:195], off
	s_add_i32 m0, s4, 0x2000
	s_add_u32 s4, s8, 0x40000
	v_lshl_add_u64 v[196:197], s[8:9], 0, v[136:137]
	s_addc_u32 s5, s9, 0
	s_add_i32 s65, s69, s14
	global_load_lds_dwordx4 v[196:197], off
	v_lshl_add_u64 v[202:203], s[4:5], 0, v[132:133]
	s_mov_b32 m0, s65
	v_lshl_add_u64 v[204:205], s[10:11], 0, v[134:135]
	global_load_lds_dwordx4 v[202:203], off
	v_lshl_add_u64 v[202:203], s[4:5], 0, v[136:137]
	s_add_i32 m0, s65, 0x2000
	s_nop 0
	global_load_lds_dwordx4 v[202:203], off
	v_lshl_add_u64 v[202:203], s[10:11], 0, v[130:131]
	s_mov_b32 m0, s1
	s_nop 0
	global_load_lds_dwordx4 v[202:203], off
	s_mov_b32 m0, s17
	s_nop 0
	global_load_lds_dwordx4 v[204:205], off
	s_waitcnt vmcnt(8)
	s_waitcnt lgkmcnt(0)
	s_barrier
; #define PG8_STAGE(bufoff, gbase, voff) do { _Pragma("unroll") for (int _i = 0; _i < 2; ++_i) \
;         __builtin_amdgcn_global_load_lds((const unsigned*)((const char*)(gbase) + (voff)[_i]), (PG8_LAS unsigned*)(lds + (bufoff) + ldsw + _i * 8192), 16, 0, 0); } while (0)
; #define PG8_LDA(dst, b, h) do { _Pragma("unroll") for (int m = 0; m < 4; ++m) _Pragma("unroll") for (int k = 0; k < 2; ++k) dst[m][k] = *(const PG8_LAS bf16x8*)(lds + PG8_SA(b, h) + aoff + m * 2048 + k * 1024); } while (0)
; #define PG8_LDB(dst, b, h) do { _Pragma("unroll") for (int n = 0; n < 2; ++n) _Pragma("unroll") for (int k = 0; k < 2; ++k) dst[n][k] = *(const PG8_LAS bf16x8*)(lds + PG8_SB(b, h) + boff + n * 2048 + k * 1024); } while (0)
; #define PG8_MMA(ai, bj, At, Bt) do { __builtin_amdgcn_s_setprio(1); _Pragma("unroll") for (int m = 0; m < 4; ++m) _Pragma("unroll") for (int n = 0; n < 2; ++n) _Pragma("unroll") for (int k = 0; k < 2; ++k) \
;         acc[ai][bj][m][n] = __builtin_amdgcn_mfma_f32_16x16x32_bf16(Bt[n][k], At[m][k], acc[ai][bj][m][n], 0, 0, 0); __builtin_amdgcn_s_setprio(0); } while (0)
; #define PG8_WAIT_V(n) asm volatile("s_waitcnt vmcnt(" #n ")" ::: "memory")
; #define PG8_WAIT_L(n) asm volatile("s_waitcnt lgkmcnt(" #n ")" ::: "memory")
; #define PG8_BAR __builtin_amdgcn_s_barrier()
; #define PG8_SCHED __builtin_amdgcn_sched_barrier(0)
; template <class Epi, class Sched, bool ALIGN_EPI = false, bool SP2 = false>
; __device__ __forceinline__ void gemm_phase(PG8_LAS unsigned char* lds, const Gemm g, const Sched& S, const Epi& E, int wv) {
;     ...
;             PG8_WAIT_V(8); PG8_WAIT_L(0); PG8_BAR; PG8_MMA(1, 0, At, B0); PG8_MMA(1, 1, At, B1); PG8_BAR; PG8_SCHED;
;             PG8_LDB(B0, 1, 0); PG8_LDB(B1, 1, 1); PG8_SCHED; PG8_LDA(At, 1, 0); PG8_STAGE(PG8_SA(0, 1), a2 + hstepA, voffA);
;             PG8_WAIT_V(8); PG8_WAIT_L(0); PG8_BAR; PG8_MMA(0, 0, At, B0); PG8_MMA(0, 1, At, B1); PG8_BAR; PG8_SCHED;
	s_setprio 1
	s_waitcnt lgkmcnt(0)
	v_mfma_f32_16x16x32_bf16 v[62:65], v[142:145], v[198:201], v[62:65]
	v_mfma_f32_16x16x32_bf16 v[58:61], v[170:173], v[198:201], v[58:61]
	v_mfma_f32_16x16x32_bf16 v[46:49], v[142:145], v[222:225], v[46:49]
	v_mfma_f32_16x16x32_bf16 v[42:45], v[170:173], v[222:225], v[42:45]
	v_mfma_f32_16x16x32_bf16 v[30:33], v[142:145], v[230:233], v[30:33]
	v_mfma_f32_16x16x32_bf16 v[26:29], v[170:173], v[230:233], v[26:29]
	v_mfma_f32_16x16x32_bf16 v[14:17], v[142:145], v[238:241], v[14:17]
	v_mfma_f32_16x16x32_bf16 v[10:13], v[170:173], v[238:241], v[10:13]
	v_mfma_f32_16x16x32_bf16 v[62:65], v[166:169], v[218:221], v[62:65]
	v_mfma_f32_16x16x32_bf16 v[58:61], v[174:177], v[218:221], v[58:61]
	v_mfma_f32_16x16x32_bf16 v[46:49], v[166:169], v[226:229], v[46:49]
	v_mfma_f32_16x16x32_bf16 v[42:45], v[174:177], v[226:229], v[42:45]
	v_mfma_f32_16x16x32_bf16 v[30:33], v[166:169], v[234:237], v[30:33]
	v_mfma_f32_16x16x32_bf16 v[26:29], v[174:177], v[234:237], v[26:29]
	v_mfma_f32_16x16x32_bf16 v[14:17], v[166:169], v[242:245], v[14:17]
	v_mfma_f32_16x16x32_bf16 v[10:13], v[174:177], v[242:245], v[10:13]
	v_mfma_f32_16x16x32_bf16 v[54:57], v[178:181], v[198:201], v[54:57]
	v_mfma_f32_16x16x32_bf16 v[50:53], v[186:189], v[198:201], v[50:53]
	v_mfma_f32_16x16x32_bf16 v[38:41], v[178:181], v[222:225], v[38:41]
	v_mfma_f32_16x16x32_bf16 v[34:37], v[186:189], v[222:225], v[34:37]
	v_mfma_f32_16x16x32_bf16 v[22:25], v[178:181], v[230:233], v[22:25]
	v_mfma_f32_16x16x32_bf16 v[18:21], v[186:189], v[230:233], v[18:21]
	v_mfma_f32_16x16x32_bf16 v[6:9], v[178:181], v[238:241], v[6:9]
	v_mfma_f32_16x16x32_bf16 v[2:5], v[186:189], v[238:241], v[2:5]
	v_mfma_f32_16x16x32_bf16 v[54:57], v[182:185], v[218:221], v[54:57]
	v_mfma_f32_16x16x32_bf16 v[50:53], v[190:193], v[218:221], v[50:53]
	v_mfma_f32_16x16x32_bf16 v[38:41], v[182:185], v[226:229], v[38:41]
	v_mfma_f32_16x16x32_bf16 v[34:37], v[190:193], v[226:229], v[34:37]
	v_mfma_f32_16x16x32_bf16 v[22:25], v[182:185], v[234:237], v[22:25]
	v_mfma_f32_16x16x32_bf16 v[18:21], v[190:193], v[234:237], v[18:21]
	v_mfma_f32_16x16x32_bf16 v[6:9], v[182:185], v[242:245], v[6:9]
	v_mfma_f32_16x16x32_bf16 v[2:5], v[190:193], v[242:245], v[2:5]
	s_setprio 0
	s_barrier
	s_add_i32 s65, 0, 0x18000
	v_add_u32_e32 v0, s65, v146
	s_add_i32 s69, 0, 0x1c000
	ds_read_b128 v[142:145], v0
	ds_read_b128 v[166:169], v0 offset:1024
	ds_read_b128 v[170:173], v0 offset:2048
	ds_read_b128 v[174:177], v0 offset:3072
	v_add_u32_e32 v0, s69, v146
	ds_read_b128 v[178:181], v0
	ds_read_b128 v[182:185], v0 offset:1024
	ds_read_b128 v[186:189], v0 offset:2048
	ds_read_b128 v[190:193], v0 offset:3072
	s_add_u32 s4, s10, 0x2c0000
	s_addc_u32 s5, s11, 0
	s_mov_b32 m0, s18
	v_lshl_add_u64 v[206:207], s[4:5], 0, v[130:131]
	ds_read_b128 v[198:201], v165 offset:32768
	ds_read_b128 v[218:221], v165 offset:33792
	ds_read_b128 v[222:225], v165 offset:34816
	ds_read_b128 v[226:229], v165 offset:35840
	ds_read_b128 v[230:233], v165 offset:36864
	ds_read_b128 v[234:237], v165 offset:37888
	ds_read_b128 v[238:241], v165 offset:38912
	ds_read_b128 v[242:245], v165 offset:39936
	global_load_lds_dwordx4 v[206:207], off
	v_lshl_add_u64 v[206:207], s[4:5], 0, v[134:135]
	s_mov_b32 m0, s19
	s_nop 0
	global_load_lds_dwordx4 v[206:207], off
	s_waitcnt vmcnt(8)
	s_waitcnt lgkmcnt(0)
	s_barrier
	s_setprio 1
	s_waitcnt lgkmcnt(0)
	v_mfma_f32_16x16x32_bf16 v[126:129], v[142:145], v[198:201], v[126:129]
	v_mfma_f32_16x16x32_bf16 v[122:125], v[170:173], v[198:201], v[122:125]
	v_mfma_f32_16x16x32_bf16 v[110:113], v[142:145], v[222:225], v[110:113]
	v_mfma_f32_16x16x32_bf16 v[106:109], v[170:173], v[222:225], v[106:109]
	v_mfma_f32_16x16x32_bf16 v[94:97], v[142:145], v[230:233], v[94:97]
	v_mfma_f32_16x16x32_bf16 v[90:93], v[170:173], v[230:233], v[90:93]
	v_mfma_f32_16x16x32_bf16 v[78:81], v[142:145], v[238:241], v[78:81]
	v_mfma_f32_16x16x32_bf16 v[74:77], v[170:173], v[238:241], v[74:77]
	v_mfma_f32_16x16x32_bf16 v[126:129], v[166:169], v[218:221], v[126:129]
	v_mfma_f32_16x16x32_bf16 v[122:125], v[174:177], v[218:221], v[122:125]
	v_mfma_f32_16x16x32_bf16 v[110:113], v[166:169], v[226:229], v[110:113]
	v_mfma_f32_16x16x32_bf16 v[106:109], v[174:177], v[226:229], v[106:109]
	v_mfma_f32_16x16x32_bf16 v[94:97], v[166:169], v[234:237], v[94:97]
	v_mfma_f32_16x16x32_bf16 v[90:93], v[174:177], v[234:237], v[90:93]
	v_mfma_f32_16x16x32_bf16 v[78:81], v[166:169], v[242:245], v[78:81]
	v_mfma_f32_16x16x32_bf16 v[74:77], v[174:177], v[242:245], v[74:77]
	v_mfma_f32_16x16x32_bf16 v[118:121], v[178:181], v[198:201], v[118:121]
	v_mfma_f32_16x16x32_bf16 v[114:117], v[186:189], v[198:201], v[114:117]
	v_mfma_f32_16x16x32_bf16 v[102:105], v[178:181], v[222:225], v[102:105]
	v_mfma_f32_16x16x32_bf16 v[98:101], v[186:189], v[222:225], v[98:101]
	v_mfma_f32_16x16x32_bf16 v[86:89], v[178:181], v[230:233], v[86:89]
	v_mfma_f32_16x16x32_bf16 v[82:85], v[186:189], v[230:233], v[82:85]
	v_mfma_f32_16x16x32_bf16 v[70:73], v[178:181], v[238:241], v[70:73]
	v_mfma_f32_16x16x32_bf16 v[66:69], v[186:189], v[238:241], v[66:69]
	v_mfma_f32_16x16x32_bf16 v[118:121], v[182:185], v[218:221], v[118:121]
	v_mfma_f32_16x16x32_bf16 v[114:117], v[190:193], v[218:221], v[114:117]
	v_mfma_f32_16x16x32_bf16 v[102:105], v[182:185], v[226:229], v[102:105]
	v_mfma_f32_16x16x32_bf16 v[98:101], v[190:193], v[226:229], v[98:101]
	v_mfma_f32_16x16x32_bf16 v[86:89], v[182:185], v[234:237], v[86:89]
	v_mfma_f32_16x16x32_bf16 v[82:85], v[190:193], v[234:237], v[82:85]
	v_mfma_f32_16x16x32_bf16 v[70:73], v[182:185], v[242:245], v[70:73]
	v_mfma_f32_16x16x32_bf16 v[66:69], v[190:193], v[242:245], v[66:69]
	s_setprio 0
	s_barrier
; #define PG8_STAGE(bufoff, gbase, voff) do { _Pragma("unroll") for (int _i = 0; _i < 2; ++_i) \
;         __builtin_amdgcn_global_load_lds((const unsigned*)((const char*)(gbase) + (voff)[_i]), (PG8_LAS unsigned*)(lds + (bufoff) + ldsw + _i * 8192), 16, 0, 0); } while (0)
; #define PG8_LDA(dst, b, h) do { _Pragma("unroll") for (int m = 0; m < 4; ++m) _Pragma("unroll") for (int k = 0; k < 2; ++k) dst[m][k] = *(const PG8_LAS bf16x8*)(lds + PG8_SA(b, h) + aoff + m * 2048 + k * 1024); } while (0)
; #define PG8_MMA(ai, bj, At, Bt) do { __builtin_amdgcn_s_setprio(1); _Pragma("unroll") for (int m = 0; m < 4; ++m) _Pragma("unroll") for (int n = 0; n < 2; ++n) _Pragma("unroll") for (int k = 0; k < 2; ++k) \
;         acc[ai][bj][m][n] = __builtin_amdgcn_mfma_f32_16x16x32_bf16(Bt[n][k], At[m][k], acc[ai][bj][m][n], 0, 0, 0); __builtin_amdgcn_s_setprio(0); } while (0)
; #define PG8_WAIT_V(n) asm volatile("s_waitcnt vmcnt(" #n ")" ::: "memory")
; #define PG8_WAIT_L(n) asm volatile("s_waitcnt lgkmcnt(" #n ")" ::: "memory")
; #define PG8_BAR __builtin_amdgcn_s_barrier()
; #define PG8_SCHED __builtin_amdgcn_sched_barrier(0)
; template <class Epi, class Sched, bool ALIGN_EPI = false, bool SP2 = false>
; __device__ __forceinline__ void gemm_phase(PG8_LAS unsigned char* lds, const Gemm g, const Sched& S, const Epi& E, int wv) {
;     ...
;         for (int t = 0; t < nt; t += 2) {
;             const bool last = (t == nt - 2);
;     ...
;             PG8_LDA(At, 1, 1); PG8_STAGE(PG8_SB(1, 0), b3, voffB); PG8_STAGE(PG8_SB(1, 1), b3 + hstepB, voffB); PG8_STAGE(PG8_SA(1, 0), a3, voffA);
;             PG8_WAIT_V(8); PG8_WAIT_L(0); PG8_BAR; PG8_MMA(1, 0, At, B0); PG8_MMA(1, 1, At, B1); PG8_BAR; PG8_SCHED;
	s_add_i32 s4, s65, s14
	v_lshl_add_u64 v[194:195], v[194:195], 0, s[20:21]
	s_mov_b32 m0, s4
	ds_read_b128 v[198:201], v165 offset:49152
	ds_read_b128 v[218:221], v165 offset:50176
	ds_read_b128 v[222:225], v165 offset:51200
	ds_read_b128 v[226:229], v165 offset:52224
	ds_read_b128 v[230:233], v165 offset:53248
	ds_read_b128 v[234:237], v165 offset:54272
	ds_read_b128 v[238:241], v165 offset:55296
	ds_read_b128 v[242:245], v165 offset:56320
	global_load_lds_dwordx4 v[194:195], off
	s_add_i32 m0, s4, 0x2000
	s_add_u32 s4, s8, 0x40080
	v_lshl_add_u64 v[194:195], v[196:197], 0, s[20:21]
	s_addc_u32 s5, s9, 0
	s_add_i32 s8, s69, s14
	global_load_lds_dwordx4 v[194:195], off
	v_lshl_add_u64 v[194:195], s[4:5], 0, v[132:133]
	s_mov_b32 m0, s8
	s_nop 0
	global_load_lds_dwordx4 v[194:195], off
	v_lshl_add_u64 v[194:195], s[4:5], 0, v[136:137]
	s_add_i32 m0, s8, 0x2000
	s_nop 0
	global_load_lds_dwordx4 v[194:195], off
	v_lshl_add_u64 v[194:195], v[202:203], 0, s[20:21]
	s_mov_b32 m0, s25
	s_nop 0
	global_load_lds_dwordx4 v[194:195], off
	v_lshl_add_u64 v[194:195], v[204:205], 0, s[20:21]
	s_mov_b32 m0, s46
	s_nop 0
	global_load_lds_dwordx4 v[194:195], off
	s_waitcnt vmcnt(8)
	s_waitcnt lgkmcnt(0)
	s_barrier
	s_setprio 1
	s_waitcnt lgkmcnt(0)
	v_mfma_f32_16x16x32_bf16 v[62:65], v[142:145], v[198:201], v[62:65]
	v_mfma_f32_16x16x32_bf16 v[58:61], v[170:173], v[198:201], v[58:61]
	v_mfma_f32_16x16x32_bf16 v[46:49], v[142:145], v[222:225], v[46:49]
	v_mfma_f32_16x16x32_bf16 v[42:45], v[170:173], v[222:225], v[42:45]
	v_mfma_f32_16x16x32_bf16 v[30:33], v[142:145], v[230:233], v[30:33]
	v_mfma_f32_16x16x32_bf16 v[26:29], v[170:173], v[230:233], v[26:29]
	v_mfma_f32_16x16x32_bf16 v[14:17], v[142:145], v[238:241], v[14:17]
	v_mfma_f32_16x16x32_bf16 v[10:13], v[170:173], v[238:241], v[10:13]
	v_mfma_f32_16x16x32_bf16 v[62:65], v[166:169], v[218:221], v[62:65]
	v_mfma_f32_16x16x32_bf16 v[58:61], v[174:177], v[218:221], v[58:61]
	v_mfma_f32_16x16x32_bf16 v[46:49], v[166:169], v[226:229], v[46:49]
	v_mfma_f32_16x16x32_bf16 v[42:45], v[174:177], v[226:229], v[42:45]
	v_mfma_f32_16x16x32_bf16 v[30:33], v[166:169], v[234:237], v[30:33]
	v_mfma_f32_16x16x32_bf16 v[26:29], v[174:177], v[234:237], v[26:29]
	v_mfma_f32_16x16x32_bf16 v[14:17], v[166:169], v[242:245], v[14:17]
	v_mfma_f32_16x16x32_bf16 v[10:13], v[174:177], v[242:245], v[10:13]
	v_mfma_f32_16x16x32_bf16 v[54:57], v[178:181], v[198:201], v[54:57]
	v_mfma_f32_16x16x32_bf16 v[50:53], v[186:189], v[198:201], v[50:53]
	v_mfma_f32_16x16x32_bf16 v[38:41], v[178:181], v[222:225], v[38:41]
	v_mfma_f32_16x16x32_bf16 v[34:37], v[186:189], v[222:225], v[34:37]
	v_mfma_f32_16x16x32_bf16 v[22:25], v[178:181], v[230:233], v[22:25]
	v_mfma_f32_16x16x32_bf16 v[18:21], v[186:189], v[230:233], v[18:21]
	v_mfma_f32_16x16x32_bf16 v[6:9], v[178:181], v[238:241], v[6:9]
	v_mfma_f32_16x16x32_bf16 v[2:5], v[186:189], v[238:241], v[2:5]
	v_mfma_f32_16x16x32_bf16 v[54:57], v[182:185], v[218:221], v[54:57]
	v_mfma_f32_16x16x32_bf16 v[50:53], v[190:193], v[218:221], v[50:53]
	v_mfma_f32_16x16x32_bf16 v[38:41], v[182:185], v[226:229], v[38:41]
	v_mfma_f32_16x16x32_bf16 v[34:37], v[190:193], v[226:229], v[34:37]
	v_mfma_f32_16x16x32_bf16 v[22:25], v[182:185], v[234:237], v[22:25]
	v_mfma_f32_16x16x32_bf16 v[18:21], v[190:193], v[234:237], v[18:21]
	v_mfma_f32_16x16x32_bf16 v[6:9], v[182:185], v[242:245], v[6:9]
	v_mfma_f32_16x16x32_bf16 v[2:5], v[190:193], v[242:245], v[2:5]
	s_setprio 0
	s_barrier
	s_add_i32 s37, s37, 2
	s_add_u32 s33, s33, 0x100
	s_addc_u32 s36, s36, 0
	s_cmp_gt_u32 s37, 13
	s_mov_b64 s[4:5], s[6:7]
	s_cbranch_scc0 .LBB0_140
	s_and_b64 vcc, exec, s[2:3]
	s_cbranch_vccz .LBB0_143
	s_barrier

; #define PG8_STAGE(bufoff, gbase, voff) do { _Pragma("unroll") for (int _i = 0; _i < 2; ++_i) \
;         __builtin_amdgcn_global_load_lds((const unsigned*)((const char*)(gbase) + (voff)[_i]), (PG8_LAS unsigned*)(lds + (bufoff) + ldsw + _i * 8192), 16, 0, 0); } while (0)
; #define PG8_LDA(dst, b, h) do { _Pragma("unroll") for (int m = 0; m < 4; ++m) _Pragma("unroll") for (int k = 0; k < 2; ++k) dst[m][k] = *(const PG8_LAS bf16x8*)(lds + PG8_SA(b, h) + aoff + m * 2048 + k * 1024); } while (0)
; #define PG8_LDB(dst, b, h) do { _Pragma("unroll") for (int n = 0; n < 2; ++n) _Pragma("unroll") for (int k = 0; k < 2; ++k) dst[n][k] = *(const PG8_LAS bf16x8*)(lds + PG8_SB(b, h) + boff + n * 2048 + k * 1024); } while (0)
; #define PG8_MMA(ai, bj, At, Bt) do { __builtin_amdgcn_s_setprio(1); _Pragma("unroll") for (int m = 0; m < 4; ++m) _Pragma("unroll") for (int n = 0; n < 2; ++n) _Pragma("unroll") for (int k = 0; k < 2; ++k) \
;         acc[ai][bj][m][n] = __builtin_amdgcn_mfma_f32_16x16x32_bf16(Bt[n][k], At[m][k], acc[ai][bj][m][n], 0, 0, 0); __builtin_amdgcn_s_setprio(0); } while (0)
; #define PG8_WAIT_V(n) asm volatile("s_waitcnt vmcnt(" #n ")" ::: "memory")
; #define PG8_WAIT_L(n) asm volatile("s_waitcnt lgkmcnt(" #n ")" ::: "memory")
; #define PG8_BAR __builtin_amdgcn_s_barrier()
; #define PG8_SCHED __builtin_amdgcn_sched_barrier(0)
; template <class Epi, class Sched, bool ALIGN_EPI = false, bool SP2 = false>
; __device__ __forceinline__ void gemm_phase(PG8_LAS unsigned char* lds, const Gemm g, const Sched& S, const Epi& E, int wv) {
;     ...
;             const bool last = (t == nt - 2);
;             const char* a1 = cA + (size_t)(t + 1) * kstep;
;             const char* a2 = last ? nA : cA + (size_t)(t + 2) * kstep; const char* b2 = last ? nB : cB + (size_t)(t + 2) * kstep;
;             const char* a3 = a2 + kstep; const char* b3 = b2 + kstep;
;             if (last && has_next) S.a_ready(nxt);
;             if constexpr (SP2) {
;             PG8_LDB(B0, 0, 0); PG8_LDB(B1, 0, 1); PG8_SCHED; PG8_LDA(At, 0, 0); PG8_STAGE(PG8_SA(1, 1), a1 + hstepA, voffA);
;             PG8_WAIT_V(8); PG8_WAIT_L(0); PG8_BAR; PG8_MMA(0, 0, At, B0); PG8_MMA(0, 1, At, B1); PG8_BAR; PG8_SCHED;
;             PG8_LDA(At, 0, 1); PG8_STAGE(PG8_SB(0, 0), b2, voffB); PG8_STAGE(PG8_SB(0, 1), b2 + hstepB, voffB); PG8_STAGE(PG8_SA(0, 0), a2, voffA);
.LBB0_266:
	s_add_u32 s14, s12, 0xfffc0080
	s_addc_u32 s15, s13, -1
	s_add_i32 s41, 0, 0x10000
	s_cmp_eq_u32 s40, 12
	s_cselect_b32 s17, s5, s15
	s_cselect_b32 s16, s18, s14
	v_add_u32_e32 v146, s41, v154
	s_cselect_b32 s15, s7, s39
	s_cselect_b32 s14, s19, s38
	s_add_i32 s46, 0, 0x14000
	ds_read_b128 v[148:151], v146
	ds_read_b128 v[164:167], v146 offset:1024
	ds_read_b128 v[168:171], v146 offset:2048
	ds_read_b128 v[172:175], v146 offset:3072
	v_add_u32_e32 v146, s46, v154
	ds_read_b128 v[176:179], v146
	ds_read_b128 v[180:183], v146 offset:1024
	ds_read_b128 v[184:187], v146 offset:2048
	ds_read_b128 v[188:191], v146 offset:3072
	v_lshl_add_u64 v[152:153], s[12:13], 0, v[142:143]
	s_add_i32 m0, s43, 0xc000
	ds_read_b128 v[198:201], v163
	ds_read_b128 v[218:221], v163 offset:1024
	ds_read_b128 v[222:225], v163 offset:2048
	ds_read_b128 v[226:229], v163 offset:3072
	ds_read_b128 v[230:233], v163 offset:4096
	ds_read_b128 v[234:237], v163 offset:5120
	ds_read_b128 v[238:241], v163 offset:6144
	ds_read_b128 v[242:245], v163 offset:7168
	global_load_lds_dwordx4 v[152:153], off
	v_lshl_add_u64 v[152:153], s[12:13], 0, v[144:145]
	s_add_i32 m0, s43, 0xe000
	s_nop 0
	global_load_lds_dwordx4 v[152:153], off
	s_waitcnt vmcnt(8)
	s_waitcnt lgkmcnt(0)
	s_barrier
	s_setprio 1
	s_waitcnt lgkmcnt(0)
	v_mfma_f32_16x16x32_bf16 v[126:129], v[148:151], v[198:201], v[126:129]
	v_mfma_f32_16x16x32_bf16 v[122:125], v[168:171], v[198:201], v[122:125]
	v_mfma_f32_16x16x32_bf16 v[110:113], v[148:151], v[222:225], v[110:113]
	v_mfma_f32_16x16x32_bf16 v[106:109], v[168:171], v[222:225], v[106:109]
	v_mfma_f32_16x16x32_bf16 v[94:97], v[148:151], v[230:233], v[94:97]
	v_mfma_f32_16x16x32_bf16 v[90:93], v[168:171], v[230:233], v[90:93]
	v_mfma_f32_16x16x32_bf16 v[78:81], v[148:151], v[238:241], v[78:81]
	v_mfma_f32_16x16x32_bf16 v[74:77], v[168:171], v[238:241], v[74:77]
	v_mfma_f32_16x16x32_bf16 v[126:129], v[164:167], v[218:221], v[126:129]
	v_mfma_f32_16x16x32_bf16 v[122:125], v[172:175], v[218:221], v[122:125]
	v_mfma_f32_16x16x32_bf16 v[110:113], v[164:167], v[226:229], v[110:113]
	v_mfma_f32_16x16x32_bf16 v[106:109], v[172:175], v[226:229], v[106:109]
	v_mfma_f32_16x16x32_bf16 v[94:97], v[164:167], v[234:237], v[94:97]
	v_mfma_f32_16x16x32_bf16 v[90:93], v[172:175], v[234:237], v[90:93]
	v_mfma_f32_16x16x32_bf16 v[78:81], v[164:167], v[242:245], v[78:81]
	v_mfma_f32_16x16x32_bf16 v[74:77], v[172:175], v[242:245], v[74:77]
	v_mfma_f32_16x16x32_bf16 v[118:121], v[176:179], v[198:201], v[118:121]
	v_mfma_f32_16x16x32_bf16 v[114:117], v[184:187], v[198:201], v[114:117]
	v_mfma_f32_16x16x32_bf16 v[102:105], v[176:179], v[222:225], v[102:105]
	v_mfma_f32_16x16x32_bf16 v[98:101], v[184:187], v[222:225], v[98:101]
	v_mfma_f32_16x16x32_bf16 v[86:89], v[176:179], v[230:233], v[86:89]
	v_mfma_f32_16x16x32_bf16 v[82:85], v[184:187], v[230:233], v[82:85]
	v_mfma_f32_16x16x32_bf16 v[70:73], v[176:179], v[238:241], v[70:73]
	v_mfma_f32_16x16x32_bf16 v[66:69], v[184:187], v[238:241], v[66:69]
	v_mfma_f32_16x16x32_bf16 v[118:121], v[180:183], v[218:221], v[118:121]
	v_mfma_f32_16x16x32_bf16 v[114:117], v[188:191], v[218:221], v[114:117]
	v_mfma_f32_16x16x32_bf16 v[102:105], v[180:183], v[226:229], v[102:105]
	v_mfma_f32_16x16x32_bf16 v[98:101], v[188:191], v[226:229], v[98:101]
	v_mfma_f32_16x16x32_bf16 v[86:89], v[180:183], v[234:237], v[86:89]
	v_mfma_f32_16x16x32_bf16 v[82:85], v[188:191], v[234:237], v[82:85]
	v_mfma_f32_16x16x32_bf16 v[70:73], v[180:183], v[242:245], v[70:73]
	v_mfma_f32_16x16x32_bf16 v[66:69], v[188:191], v[242:245], v[66:69]
	s_setprio 0
	s_barrier
	s_add_i32 s41, s41, s79
	v_lshl_add_u64 v[152:153], s[14:15], 0, v[132:133]
	s_mov_b32 m0, s41
	ds_read_b128 v[198:201], v163 offset:16384
	ds_read_b128 v[218:221], v163 offset:17408
	ds_read_b128 v[222:225], v163 offset:18432
	ds_read_b128 v[226:229], v163 offset:19456
	ds_read_b128 v[230:233], v163 offset:20480
	ds_read_b128 v[234:237], v163 offset:21504
	ds_read_b128 v[238:241], v163 offset:22528
	ds_read_b128 v[242:245], v163 offset:23552
	global_load_lds_dwordx4 v[152:153], off
	s_add_i32 m0, s41, 0x2000
	s_add_u32 vcc_lo, s14, 0x40000
	v_lshl_add_u64 v[192:193], s[14:15], 0, v[136:137]
	s_addc_u32 vcc_hi, s15, 0
	s_add_i32 s41, s46, s79
	global_load_lds_dwordx4 v[192:193], off
	v_lshl_add_u64 v[194:195], vcc, 0, v[132:133]
	s_mov_b32 m0, s41
	v_lshl_add_u64 v[196:197], s[16:17], 0, v[134:135]
	global_load_lds_dwordx4 v[194:195], off
	v_lshl_add_u64 v[194:195], vcc, 0, v[136:137]
	s_add_i32 m0, s41, 0x2000
	s_nop 0
	global_load_lds_dwordx4 v[194:195], off
	v_lshl_add_u64 v[194:195], s[16:17], 0, v[130:131]
	s_mov_b32 m0, s43
	s_nop 0
	global_load_lds_dwordx4 v[194:195], off
	s_mov_b32 m0, s65
	s_nop 0
	global_load_lds_dwordx4 v[196:197], off
	s_waitcnt vmcnt(8)
	s_waitcnt lgkmcnt(0)
	s_barrier
; #define PG8_STAGE(bufoff, gbase, voff) do { _Pragma("unroll") for (int _i = 0; _i < 2; ++_i) \
;         __builtin_amdgcn_global_load_lds((const unsigned*)((const char*)(gbase) + (voff)[_i]), (PG8_LAS unsigned*)(lds + (bufoff) + ldsw + _i * 8192), 16, 0, 0); } while (0)
; #define PG8_LDA(dst, b, h) do { _Pragma("unroll") for (int m = 0; m < 4; ++m) _Pragma("unroll") for (int k = 0; k < 2; ++k) dst[m][k] = *(const PG8_LAS bf16x8*)(lds + PG8_SA(b, h) + aoff + m * 2048 + k * 1024); } while (0)
; #define PG8_LDB(dst, b, h) do { _Pragma("unroll") for (int n = 0; n < 2; ++n) _Pragma("unroll") for (int k = 0; k < 2; ++k) dst[n][k] = *(const PG8_LAS bf16x8*)(lds + PG8_SB(b, h) + boff + n * 2048 + k * 1024); } while (0)
; #define PG8_MMA(ai, bj, At, Bt) do { __builtin_amdgcn_s_setprio(1); _Pragma("unroll") for (int m = 0; m < 4; ++m) _Pragma("unroll") for (int n = 0; n < 2; ++n) _Pragma("unroll") for (int k = 0; k < 2; ++k) \
;         acc[ai][bj][m][n] = __builtin_amdgcn_mfma_f32_16x16x32_bf16(Bt[n][k], At[m][k], acc[ai][bj][m][n], 0, 0, 0); __builtin_amdgcn_s_setprio(0); } while (0)
; #define PG8_WAIT_V(n) asm volatile("s_waitcnt vmcnt(" #n ")" ::: "memory")
; #define PG8_WAIT_L(n) asm volatile("s_waitcnt lgkmcnt(" #n ")" ::: "memory")
; #define PG8_BAR __builtin_amdgcn_s_barrier()
; #define PG8_SCHED __builtin_amdgcn_sched_barrier(0)
; template <class Epi, class Sched, bool ALIGN_EPI = false, bool SP2 = false>
; __device__ __forceinline__ void gemm_phase(PG8_LAS unsigned char* lds, const Gemm g, const Sched& S, const Epi& E, int wv) {
;     ...
;             PG8_WAIT_V(8); PG8_WAIT_L(0); PG8_BAR; PG8_MMA(1, 0, At, B0); PG8_MMA(1, 1, At, B1); PG8_BAR; PG8_SCHED;
;             PG8_LDB(B0, 1, 0); PG8_LDB(B1, 1, 1); PG8_SCHED; PG8_LDA(At, 1, 0); PG8_STAGE(PG8_SA(0, 1), a2 + hstepA, voffA);
;             PG8_WAIT_V(8); PG8_WAIT_L(0); PG8_BAR; PG8_MMA(0, 0, At, B0); PG8_MMA(0, 1, At, B1); PG8_BAR; PG8_SCHED;
	s_setprio 1
	s_waitcnt lgkmcnt(0)
	v_mfma_f32_16x16x32_bf16 v[62:65], v[148:151], v[198:201], v[62:65]
	v_mfma_f32_16x16x32_bf16 v[58:61], v[168:171], v[198:201], v[58:61]
	v_mfma_f32_16x16x32_bf16 v[46:49], v[148:151], v[222:225], v[46:49]
	v_mfma_f32_16x16x32_bf16 v[42:45], v[168:171], v[222:225], v[42:45]
	v_mfma_f32_16x16x32_bf16 v[30:33], v[148:151], v[230:233], v[30:33]
	v_mfma_f32_16x16x32_bf16 v[26:29], v[168:171], v[230:233], v[26:29]
	v_mfma_f32_16x16x32_bf16 v[14:17], v[148:151], v[238:241], v[14:17]
	v_mfma_f32_16x16x32_bf16 v[10:13], v[168:171], v[238:241], v[10:13]
	v_mfma_f32_16x16x32_bf16 v[62:65], v[164:167], v[218:221], v[62:65]
	v_mfma_f32_16x16x32_bf16 v[58:61], v[172:175], v[218:221], v[58:61]
	v_mfma_f32_16x16x32_bf16 v[46:49], v[164:167], v[226:229], v[46:49]
	v_mfma_f32_16x16x32_bf16 v[42:45], v[172:175], v[226:229], v[42:45]
	v_mfma_f32_16x16x32_bf16 v[30:33], v[164:167], v[234:237], v[30:33]
	v_mfma_f32_16x16x32_bf16 v[26:29], v[172:175], v[234:237], v[26:29]
	v_mfma_f32_16x16x32_bf16 v[14:17], v[164:167], v[242:245], v[14:17]
	v_mfma_f32_16x16x32_bf16 v[10:13], v[172:175], v[242:245], v[10:13]
	v_mfma_f32_16x16x32_bf16 v[54:57], v[176:179], v[198:201], v[54:57]
	v_mfma_f32_16x16x32_bf16 v[50:53], v[184:187], v[198:201], v[50:53]
	v_mfma_f32_16x16x32_bf16 v[38:41], v[176:179], v[222:225], v[38:41]
	v_mfma_f32_16x16x32_bf16 v[34:37], v[184:187], v[222:225], v[34:37]
	v_mfma_f32_16x16x32_bf16 v[22:25], v[176:179], v[230:233], v[22:25]
	v_mfma_f32_16x16x32_bf16 v[18:21], v[184:187], v[230:233], v[18:21]
	v_mfma_f32_16x16x32_bf16 v[6:9], v[176:179], v[238:241], v[6:9]
	v_mfma_f32_16x16x32_bf16 v[2:5], v[184:187], v[238:241], v[2:5]
	v_mfma_f32_16x16x32_bf16 v[54:57], v[180:183], v[218:221], v[54:57]
	v_mfma_f32_16x16x32_bf16 v[50:53], v[188:191], v[218:221], v[50:53]
	v_mfma_f32_16x16x32_bf16 v[38:41], v[180:183], v[226:229], v[38:41]
	v_mfma_f32_16x16x32_bf16 v[34:37], v[188:191], v[226:229], v[34:37]
	v_mfma_f32_16x16x32_bf16 v[22:25], v[180:183], v[234:237], v[22:25]
	v_mfma_f32_16x16x32_bf16 v[18:21], v[188:191], v[234:237], v[18:21]
	v_mfma_f32_16x16x32_bf16 v[6:9], v[180:183], v[242:245], v[6:9]
	v_mfma_f32_16x16x32_bf16 v[2:5], v[188:191], v[242:245], v[2:5]
	s_setprio 0
	s_barrier
	s_add_i32 s41, 0, 0x18000
	v_add_u32_e32 v146, s41, v154
	s_add_i32 s46, 0, 0x1c000
	ds_read_b128 v[148:151], v146
	ds_read_b128 v[164:167], v146 offset:1024
	ds_read_b128 v[168:171], v146 offset:2048
	ds_read_b128 v[172:175], v146 offset:3072
	v_add_u32_e32 v146, s46, v154
	ds_read_b128 v[176:179], v146
	ds_read_b128 v[180:183], v146 offset:1024
	ds_read_b128 v[184:187], v146 offset:2048
	ds_read_b128 v[188:191], v146 offset:3072
	s_add_u32 s16, s16, 0x40000
	s_addc_u32 s17, s17, 0
	s_mov_b32 m0, s24
	v_lshl_add_u64 v[202:203], s[16:17], 0, v[130:131]
	ds_read_b128 v[198:201], v163 offset:32768
	ds_read_b128 v[218:221], v163 offset:33792
	ds_read_b128 v[222:225], v163 offset:34816
	ds_read_b128 v[226:229], v163 offset:35840
	ds_read_b128 v[230:233], v163 offset:36864
	ds_read_b128 v[234:237], v163 offset:37888
	ds_read_b128 v[238:241], v163 offset:38912
	ds_read_b128 v[242:245], v163 offset:39936
	global_load_lds_dwordx4 v[202:203], off
	v_lshl_add_u64 v[202:203], s[16:17], 0, v[134:135]
	s_mov_b32 m0, s77
	s_nop 0
	global_load_lds_dwordx4 v[202:203], off
	s_waitcnt vmcnt(8)
	s_waitcnt lgkmcnt(0)
	s_barrier
	s_setprio 1
	s_waitcnt lgkmcnt(0)
	v_mfma_f32_16x16x32_bf16 v[126:129], v[148:151], v[198:201], v[126:129]
	v_mfma_f32_16x16x32_bf16 v[122:125], v[168:171], v[198:201], v[122:125]
	v_mfma_f32_16x16x32_bf16 v[110:113], v[148:151], v[222:225], v[110:113]
	v_mfma_f32_16x16x32_bf16 v[106:109], v[168:171], v[222:225], v[106:109]
	v_mfma_f32_16x16x32_bf16 v[94:97], v[148:151], v[230:233], v[94:97]
	v_mfma_f32_16x16x32_bf16 v[90:93], v[168:171], v[230:233], v[90:93]
	v_mfma_f32_16x16x32_bf16 v[78:81], v[148:151], v[238:241], v[78:81]
	v_mfma_f32_16x16x32_bf16 v[74:77], v[168:171], v[238:241], v[74:77]
	v_mfma_f32_16x16x32_bf16 v[126:129], v[164:167], v[218:221], v[126:129]
	v_mfma_f32_16x16x32_bf16 v[122:125], v[172:175], v[218:221], v[122:125]
	v_mfma_f32_16x16x32_bf16 v[110:113], v[164:167], v[226:229], v[110:113]
	v_mfma_f32_16x16x32_bf16 v[106:109], v[172:175], v[226:229], v[106:109]
	v_mfma_f32_16x16x32_bf16 v[94:97], v[164:167], v[234:237], v[94:97]
	v_mfma_f32_16x16x32_bf16 v[90:93], v[172:175], v[234:237], v[90:93]
	v_mfma_f32_16x16x32_bf16 v[78:81], v[164:167], v[242:245], v[78:81]
	v_mfma_f32_16x16x32_bf16 v[74:77], v[172:175], v[242:245], v[74:77]
	v_mfma_f32_16x16x32_bf16 v[118:121], v[176:179], v[198:201], v[118:121]
	v_mfma_f32_16x16x32_bf16 v[114:117], v[184:187], v[198:201], v[114:117]
	v_mfma_f32_16x16x32_bf16 v[102:105], v[176:179], v[222:225], v[102:105]
	v_mfma_f32_16x16x32_bf16 v[98:101], v[184:187], v[222:225], v[98:101]
	v_mfma_f32_16x16x32_bf16 v[86:89], v[176:179], v[230:233], v[86:89]
	v_mfma_f32_16x16x32_bf16 v[82:85], v[184:187], v[230:233], v[82:85]
	v_mfma_f32_16x16x32_bf16 v[70:73], v[176:179], v[238:241], v[70:73]
	v_mfma_f32_16x16x32_bf16 v[66:69], v[184:187], v[238:241], v[66:69]
	v_mfma_f32_16x16x32_bf16 v[118:121], v[180:183], v[218:221], v[118:121]
	v_mfma_f32_16x16x32_bf16 v[114:117], v[188:191], v[218:221], v[114:117]
	v_mfma_f32_16x16x32_bf16 v[102:105], v[180:183], v[226:229], v[102:105]
	v_mfma_f32_16x16x32_bf16 v[98:101], v[188:191], v[226:229], v[98:101]
	v_mfma_f32_16x16x32_bf16 v[86:89], v[180:183], v[234:237], v[86:89]
	v_mfma_f32_16x16x32_bf16 v[82:85], v[188:191], v[234:237], v[82:85]
	v_mfma_f32_16x16x32_bf16 v[70:73], v[180:183], v[242:245], v[70:73]
	v_mfma_f32_16x16x32_bf16 v[66:69], v[188:191], v[242:245], v[66:69]
	s_setprio 0
	s_barrier
; #define PG8_STAGE(bufoff, gbase, voff) do { _Pragma("unroll") for (int _i = 0; _i < 2; ++_i) \
;         __builtin_amdgcn_global_load_lds((const unsigned*)((const char*)(gbase) + (voff)[_i]), (PG8_LAS unsigned*)(lds + (bufoff) + ldsw + _i * 8192), 16, 0, 0); } while (0)
; #define PG8_LDA(dst, b, h) do { _Pragma("unroll") for (int m = 0; m < 4; ++m) _Pragma("unroll") for (int k = 0; k < 2; ++k) dst[m][k] = *(const PG8_LAS bf16x8*)(lds + PG8_SA(b, h) + aoff + m * 2048 + k * 1024); } while (0)
; #define PG8_MMA(ai, bj, At, Bt) do { __builtin_amdgcn_s_setprio(1); _Pragma("unroll") for (int m = 0; m < 4; ++m) _Pragma("unroll") for (int n = 0; n < 2; ++n) _Pragma("unroll") for (int k = 0; k < 2; ++k) \
;         acc[ai][bj][m][n] = __builtin_amdgcn_mfma_f32_16x16x32_bf16(Bt[n][k], At[m][k], acc[ai][bj][m][n], 0, 0, 0); __builtin_amdgcn_s_setprio(0); } while (0)
; #define PG8_WAIT_V(n) asm volatile("s_waitcnt vmcnt(" #n ")" ::: "memory")
; #define PG8_WAIT_L(n) asm volatile("s_waitcnt lgkmcnt(" #n ")" ::: "memory")
; #define PG8_BAR __builtin_amdgcn_s_barrier()
; #define PG8_SCHED __builtin_amdgcn_sched_barrier(0)
; template <class Epi, class Sched, bool ALIGN_EPI = false, bool SP2 = false>
; __device__ __forceinline__ void gemm_phase(PG8_LAS unsigned char* lds, const Gemm g, const Sched& S, const Epi& E, int wv) {
;     ...
;         for (int t = 0; t < nt; t += 2) {
;             const bool last = (t == nt - 2);
;     ...
;             PG8_LDA(At, 1, 1); PG8_STAGE(PG8_SB(1, 0), b3, voffB); PG8_STAGE(PG8_SB(1, 1), b3 + hstepB, voffB); PG8_STAGE(PG8_SA(1, 0), a3, voffA);
;             PG8_WAIT_V(8); PG8_WAIT_L(0); PG8_BAR; PG8_MMA(1, 0, At, B0); PG8_MMA(1, 1, At, B1); PG8_BAR; PG8_SCHED;
	s_add_i32 s16, s41, s79
	v_lshl_add_u64 v[152:153], v[152:153], 0, s[20:21]
	s_mov_b32 m0, s16
	ds_read_b128 v[198:201], v163 offset:49152
	ds_read_b128 v[218:221], v163 offset:50176
	ds_read_b128 v[222:225], v163 offset:51200
	ds_read_b128 v[226:229], v163 offset:52224
	ds_read_b128 v[230:233], v163 offset:53248
	ds_read_b128 v[234:237], v163 offset:54272
	ds_read_b128 v[238:241], v163 offset:55296
	ds_read_b128 v[242:245], v163 offset:56320
	global_load_lds_dwordx4 v[152:153], off
	s_add_i32 m0, s16, 0x2000
	s_add_u32 s14, s14, 0x40080
	v_lshl_add_u64 v[152:153], v[192:193], 0, s[20:21]
	s_addc_u32 s15, s15, 0
	s_add_i32 s16, s46, s79
	global_load_lds_dwordx4 v[152:153], off
	v_lshl_add_u64 v[152:153], s[14:15], 0, v[132:133]
	s_mov_b32 m0, s16
	s_nop 0
	global_load_lds_dwordx4 v[152:153], off
	v_lshl_add_u64 v[152:153], s[14:15], 0, v[136:137]
	s_add_i32 m0, s16, 0x2000
	s_nop 0
	global_load_lds_dwordx4 v[152:153], off
	v_lshl_add_u64 v[152:153], v[194:195], 0, s[20:21]
	s_mov_b32 m0, s30
	s_nop 0
	global_load_lds_dwordx4 v[152:153], off
	v_lshl_add_u64 v[152:153], v[196:197], 0, s[20:21]
	s_mov_b32 m0, s31
	s_nop 0
	global_load_lds_dwordx4 v[152:153], off
	s_waitcnt vmcnt(8)
	s_waitcnt lgkmcnt(0)
	s_barrier
	s_setprio 1
	s_waitcnt lgkmcnt(0)
	v_mfma_f32_16x16x32_bf16 v[62:65], v[148:151], v[198:201], v[62:65]
	v_mfma_f32_16x16x32_bf16 v[58:61], v[168:171], v[198:201], v[58:61]
	v_mfma_f32_16x16x32_bf16 v[46:49], v[148:151], v[222:225], v[46:49]
	v_mfma_f32_16x16x32_bf16 v[42:45], v[168:171], v[222:225], v[42:45]
	v_mfma_f32_16x16x32_bf16 v[30:33], v[148:151], v[230:233], v[30:33]
	v_mfma_f32_16x16x32_bf16 v[26:29], v[168:171], v[230:233], v[26:29]
	v_mfma_f32_16x16x32_bf16 v[14:17], v[148:151], v[238:241], v[14:17]
	v_mfma_f32_16x16x32_bf16 v[10:13], v[168:171], v[238:241], v[10:13]
	v_mfma_f32_16x16x32_bf16 v[62:65], v[164:167], v[218:221], v[62:65]
	v_mfma_f32_16x16x32_bf16 v[58:61], v[172:175], v[218:221], v[58:61]
	v_mfma_f32_16x16x32_bf16 v[46:49], v[164:167], v[226:229], v[46:49]
	v_mfma_f32_16x16x32_bf16 v[42:45], v[172:175], v[226:229], v[42:45]
	v_mfma_f32_16x16x32_bf16 v[30:33], v[164:167], v[234:237], v[30:33]
	v_mfma_f32_16x16x32_bf16 v[26:29], v[172:175], v[234:237], v[26:29]
	v_mfma_f32_16x16x32_bf16 v[14:17], v[164:167], v[242:245], v[14:17]
	v_mfma_f32_16x16x32_bf16 v[10:13], v[172:175], v[242:245], v[10:13]
	v_mfma_f32_16x16x32_bf16 v[54:57], v[176:179], v[198:201], v[54:57]
	v_mfma_f32_16x16x32_bf16 v[50:53], v[184:187], v[198:201], v[50:53]
	v_mfma_f32_16x16x32_bf16 v[38:41], v[176:179], v[222:225], v[38:41]
	v_mfma_f32_16x16x32_bf16 v[34:37], v[184:187], v[222:225], v[34:37]
	v_mfma_f32_16x16x32_bf16 v[22:25], v[176:179], v[230:233], v[22:25]
	v_mfma_f32_16x16x32_bf16 v[18:21], v[184:187], v[230:233], v[18:21]
	v_mfma_f32_16x16x32_bf16 v[6:9], v[176:179], v[238:241], v[6:9]
	v_mfma_f32_16x16x32_bf16 v[2:5], v[184:187], v[238:241], v[2:5]
	v_mfma_f32_16x16x32_bf16 v[54:57], v[180:183], v[218:221], v[54:57]
	v_mfma_f32_16x16x32_bf16 v[50:53], v[188:191], v[218:221], v[50:53]
	v_mfma_f32_16x16x32_bf16 v[38:41], v[180:183], v[226:229], v[38:41]
	v_mfma_f32_16x16x32_bf16 v[34:37], v[188:191], v[226:229], v[34:37]
	v_mfma_f32_16x16x32_bf16 v[22:25], v[180:183], v[234:237], v[22:25]
	v_mfma_f32_16x16x32_bf16 v[18:21], v[188:191], v[234:237], v[18:21]
	v_mfma_f32_16x16x32_bf16 v[6:9], v[180:183], v[242:245], v[6:9]
	v_mfma_f32_16x16x32_bf16 v[2:5], v[188:191], v[242:245], v[2:5]
	s_setprio 0
	s_barrier
	s_add_i32 s40, s40, 2
	s_add_u32 s12, s12, 0x100
	s_addc_u32 s13, s13, 0
	s_add_u32 s38, s38, 0x100
	s_addc_u32 s39, s39, 0
	s_cmp_gt_u32 s40, 13
	s_cbranch_scc0 .LBB0_266
	s_and_b64 vcc, exec, s[2:3]
	s_cbranch_vccz .LBB0_269
	s_barrier

; #define PG8_STAGE(bufoff, gbase, voff) do { _Pragma("unroll") for (int _i = 0; _i < 2; ++_i) \
;         __builtin_amdgcn_global_load_lds((const unsigned*)((const char*)(gbase) + (voff)[_i]), (PG8_LAS unsigned*)(lds + (bufoff) + ldsw + _i * 8192), 16, 0, 0); } while (0)
; #define PG8_LDA(dst, b, h) do { _Pragma("unroll") for (int m = 0; m < 4; ++m) _Pragma("unroll") for (int k = 0; k < 2; ++k) dst[m][k] = *(const PG8_LAS bf16x8*)(lds + PG8_SA(b, h) + aoff + m * 2048 + k * 1024); } while (0)
; #define PG8_LDB(dst, b, h) do { _Pragma("unroll") for (int n = 0; n < 2; ++n) _Pragma("unroll") for (int k = 0; k < 2; ++k) dst[n][k] = *(const PG8_LAS bf16x8*)(lds + PG8_SB(b, h) + boff + n * 2048 + k * 1024); } while (0)
; #define PG8_MMA(ai, bj, At, Bt) do { __builtin_amdgcn_s_setprio(1); _Pragma("unroll") for (int m = 0; m < 4; ++m) _Pragma("unroll") for (int n = 0; n < 2; ++n) _Pragma("unroll") for (int k = 0; k < 2; ++k) \
;         acc[ai][bj][m][n] = __builtin_amdgcn_mfma_f32_16x16x32_bf16(Bt[n][k], At[m][k], acc[ai][bj][m][n], 0, 0, 0); __builtin_amdgcn_s_setprio(0); } while (0)
; #define PG8_WAIT_V(n) asm volatile("s_waitcnt vmcnt(" #n ")" ::: "memory")
; #define PG8_WAIT_L(n) asm volatile("s_waitcnt lgkmcnt(" #n ")" ::: "memory")
; #define PG8_BAR __builtin_amdgcn_s_barrier()
; #define PG8_SCHED __builtin_amdgcn_sched_barrier(0)
; template <class Epi, class Sched, bool ALIGN_EPI = false, bool SP2 = false>
; __device__ __forceinline__ void gemm_phase(PG8_LAS unsigned char* lds, const Gemm g, const Sched& S, const Epi& E, int wv) {
;     ...
;             const bool last = (t == nt - 2);
;             const char* a1 = cA + (size_t)(t + 1) * kstep;
;             const char* a2 = last ? nA : cA + (size_t)(t + 2) * kstep; const char* b2 = last ? nB : cB + (size_t)(t + 2) * kstep;
;             const char* a3 = a2 + kstep; const char* b3 = b2 + kstep;
;             if (last && has_next) S.a_ready(nxt);
;             if constexpr (SP2) {
;             PG8_LDB(B0, 0, 0); PG8_LDB(B1, 0, 1); PG8_SCHED; PG8_LDA(At, 0, 0); PG8_STAGE(PG8_SA(1, 1), a1 + hstepA, voffA);
;             PG8_WAIT_V(8); PG8_WAIT_L(0); PG8_BAR; PG8_MMA(0, 0, At, B0); PG8_MMA(0, 1, At, B1); PG8_BAR; PG8_SCHED;
;             PG8_LDA(At, 0, 1); PG8_STAGE(PG8_SB(0, 0), b2, voffB); PG8_STAGE(PG8_SB(0, 1), b2 + hstepB, voffB); PG8_STAGE(PG8_SA(0, 0), a2, voffA);
.LBB0_358:
	s_add_u32 s14, s12, 0xfffc0080
	s_addc_u32 s15, s13, -1
	s_add_i32 s74, 0, 0x10000
	s_cmp_eq_u32 s73, 12
	s_cselect_b32 s17, s11, s15
	s_cselect_b32 s16, s46, s14
	v_add_u32_e32 v0, s74, v149
	s_cselect_b32 s15, s1, s72
	s_cselect_b32 s14, s67, s69
	s_add_i32 s76, 0, 0x14000
	ds_read_b128 v[150:153], v0
	ds_read_b128 v[166:169], v0 offset:1024
	ds_read_b128 v[170:173], v0 offset:2048
	ds_read_b128 v[174:177], v0 offset:3072
	v_add_u32_e32 v0, s76, v149
	ds_read_b128 v[178:181], v0
	ds_read_b128 v[182:185], v0 offset:1024
	ds_read_b128 v[186:189], v0 offset:2048
	ds_read_b128 v[190:193], v0 offset:3072
	v_lshl_add_u64 v[154:155], s[12:13], 0, v[144:145]
	s_add_i32 m0, s31, 0xc000
	ds_read_b128 v[198:201], v164
	ds_read_b128 v[218:221], v164 offset:1024
	ds_read_b128 v[222:225], v164 offset:2048
	ds_read_b128 v[226:229], v164 offset:3072
	ds_read_b128 v[230:233], v164 offset:4096
	ds_read_b128 v[234:237], v164 offset:5120
	ds_read_b128 v[238:241], v164 offset:6144
	ds_read_b128 v[242:245], v164 offset:7168
	global_load_lds_dwordx4 v[154:155], off
	v_lshl_add_u64 v[154:155], s[12:13], 0, v[146:147]
	s_add_i32 m0, s31, 0xe000
	s_nop 0
	global_load_lds_dwordx4 v[154:155], off
	s_waitcnt vmcnt(8)
	s_waitcnt lgkmcnt(0)
	s_barrier
	s_setprio 1
	s_waitcnt lgkmcnt(0)
	v_mfma_f32_16x16x32_bf16 v[126:129], v[150:153], v[198:201], v[126:129]
	v_mfma_f32_16x16x32_bf16 v[122:125], v[170:173], v[198:201], v[122:125]
	v_mfma_f32_16x16x32_bf16 v[110:113], v[150:153], v[222:225], v[110:113]
	v_mfma_f32_16x16x32_bf16 v[106:109], v[170:173], v[222:225], v[106:109]
	v_mfma_f32_16x16x32_bf16 v[94:97], v[150:153], v[230:233], v[94:97]
	v_mfma_f32_16x16x32_bf16 v[90:93], v[170:173], v[230:233], v[90:93]
	v_mfma_f32_16x16x32_bf16 v[78:81], v[150:153], v[238:241], v[78:81]
	v_mfma_f32_16x16x32_bf16 v[74:77], v[170:173], v[238:241], v[74:77]
	v_mfma_f32_16x16x32_bf16 v[126:129], v[166:169], v[218:221], v[126:129]
	v_mfma_f32_16x16x32_bf16 v[122:125], v[174:177], v[218:221], v[122:125]
	v_mfma_f32_16x16x32_bf16 v[110:113], v[166:169], v[226:229], v[110:113]
	v_mfma_f32_16x16x32_bf16 v[106:109], v[174:177], v[226:229], v[106:109]
	v_mfma_f32_16x16x32_bf16 v[94:97], v[166:169], v[234:237], v[94:97]
	v_mfma_f32_16x16x32_bf16 v[90:93], v[174:177], v[234:237], v[90:93]
	v_mfma_f32_16x16x32_bf16 v[78:81], v[166:169], v[242:245], v[78:81]
	v_mfma_f32_16x16x32_bf16 v[74:77], v[174:177], v[242:245], v[74:77]
	v_mfma_f32_16x16x32_bf16 v[118:121], v[178:181], v[198:201], v[118:121]
	v_mfma_f32_16x16x32_bf16 v[114:117], v[186:189], v[198:201], v[114:117]
	v_mfma_f32_16x16x32_bf16 v[102:105], v[178:181], v[222:225], v[102:105]
	v_mfma_f32_16x16x32_bf16 v[98:101], v[186:189], v[222:225], v[98:101]
	v_mfma_f32_16x16x32_bf16 v[86:89], v[178:181], v[230:233], v[86:89]
	v_mfma_f32_16x16x32_bf16 v[82:85], v[186:189], v[230:233], v[82:85]
	v_mfma_f32_16x16x32_bf16 v[70:73], v[178:181], v[238:241], v[70:73]
	v_mfma_f32_16x16x32_bf16 v[66:69], v[186:189], v[238:241], v[66:69]
	v_mfma_f32_16x16x32_bf16 v[118:121], v[182:185], v[218:221], v[118:121]
	v_mfma_f32_16x16x32_bf16 v[114:117], v[190:193], v[218:221], v[114:117]
	v_mfma_f32_16x16x32_bf16 v[102:105], v[182:185], v[226:229], v[102:105]
	v_mfma_f32_16x16x32_bf16 v[98:101], v[190:193], v[226:229], v[98:101]
	v_mfma_f32_16x16x32_bf16 v[86:89], v[182:185], v[234:237], v[86:89]
	v_mfma_f32_16x16x32_bf16 v[82:85], v[190:193], v[234:237], v[82:85]
	v_mfma_f32_16x16x32_bf16 v[70:73], v[182:185], v[242:245], v[70:73]
	v_mfma_f32_16x16x32_bf16 v[66:69], v[190:193], v[242:245], v[66:69]
	s_setprio 0
	s_barrier
	s_add_i32 s74, s74, s25
	v_lshl_add_u64 v[154:155], s[14:15], 0, v[132:133]
	s_mov_b32 m0, s74
	ds_read_b128 v[198:201], v164 offset:16384
	ds_read_b128 v[218:221], v164 offset:17408
	ds_read_b128 v[222:225], v164 offset:18432
	ds_read_b128 v[226:229], v164 offset:19456
	ds_read_b128 v[230:233], v164 offset:20480
	ds_read_b128 v[234:237], v164 offset:21504
	ds_read_b128 v[238:241], v164 offset:22528
	ds_read_b128 v[242:245], v164 offset:23552
	global_load_lds_dwordx4 v[154:155], off
	s_add_i32 m0, s74, 0x2000
	s_add_u32 s74, s14, 0x40000
	v_lshl_add_u64 v[194:195], s[14:15], 0, v[136:137]
	s_addc_u32 s75, s15, 0
	s_add_i32 s76, s76, s25
	global_load_lds_dwordx4 v[194:195], off
	v_lshl_add_u64 v[196:197], s[74:75], 0, v[132:133]
	s_mov_b32 m0, s76
	v_lshl_add_u64 v[202:203], s[16:17], 0, v[134:135]
	global_load_lds_dwordx4 v[196:197], off
	v_lshl_add_u64 v[196:197], s[74:75], 0, v[136:137]
	s_add_i32 m0, s76, 0x2000
	s_nop 0
	global_load_lds_dwordx4 v[196:197], off
	v_lshl_add_u64 v[196:197], s[16:17], 0, v[130:131]
	s_mov_b32 m0, s31
	s_nop 0
	global_load_lds_dwordx4 v[196:197], off
	s_mov_b32 m0, s33
	s_nop 0
	global_load_lds_dwordx4 v[202:203], off
	s_waitcnt vmcnt(8)
	s_waitcnt lgkmcnt(0)
	s_barrier
; #define PG8_STAGE(bufoff, gbase, voff) do { _Pragma("unroll") for (int _i = 0; _i < 2; ++_i) \
;         __builtin_amdgcn_global_load_lds((const unsigned*)((const char*)(gbase) + (voff)[_i]), (PG8_LAS unsigned*)(lds + (bufoff) + ldsw + _i * 8192), 16, 0, 0); } while (0)
; #define PG8_LDA(dst, b, h) do { _Pragma("unroll") for (int m = 0; m < 4; ++m) _Pragma("unroll") for (int k = 0; k < 2; ++k) dst[m][k] = *(const PG8_LAS bf16x8*)(lds + PG8_SA(b, h) + aoff + m * 2048 + k * 1024); } while (0)
; #define PG8_LDB(dst, b, h) do { _Pragma("unroll") for (int n = 0; n < 2; ++n) _Pragma("unroll") for (int k = 0; k < 2; ++k) dst[n][k] = *(const PG8_LAS bf16x8*)(lds + PG8_SB(b, h) + boff + n * 2048 + k * 1024); } while (0)
; #define PG8_MMA(ai, bj, At, Bt) do { __builtin_amdgcn_s_setprio(1); _Pragma("unroll") for (int m = 0; m < 4; ++m) _Pragma("unroll") for (int n = 0; n < 2; ++n) _Pragma("unroll") for (int k = 0; k < 2; ++k) \
;         acc[ai][bj][m][n] = __builtin_amdgcn_mfma_f32_16x16x32_bf16(Bt[n][k], At[m][k], acc[ai][bj][m][n], 0, 0, 0); __builtin_amdgcn_s_setprio(0); } while (0)
; #define PG8_WAIT_V(n) asm volatile("s_waitcnt vmcnt(" #n ")" ::: "memory")
; #define PG8_WAIT_L(n) asm volatile("s_waitcnt lgkmcnt(" #n ")" ::: "memory")
; #define PG8_BAR __builtin_amdgcn_s_barrier()
; #define PG8_SCHED __builtin_amdgcn_sched_barrier(0)
; template <class Epi, class Sched, bool ALIGN_EPI = false, bool SP2 = false>
; __device__ __forceinline__ void gemm_phase(PG8_LAS unsigned char* lds, const Gemm g, const Sched& S, const Epi& E, int wv) {
;     ...
;             PG8_WAIT_V(8); PG8_WAIT_L(0); PG8_BAR; PG8_MMA(1, 0, At, B0); PG8_MMA(1, 1, At, B1); PG8_BAR; PG8_SCHED;
;             PG8_LDB(B0, 1, 0); PG8_LDB(B1, 1, 1); PG8_SCHED; PG8_LDA(At, 1, 0); PG8_STAGE(PG8_SA(0, 1), a2 + hstepA, voffA);
;             PG8_WAIT_V(8); PG8_WAIT_L(0); PG8_BAR; PG8_MMA(0, 0, At, B0); PG8_MMA(0, 1, At, B1); PG8_BAR; PG8_SCHED;
	s_setprio 1
	s_waitcnt lgkmcnt(0)
	v_mfma_f32_16x16x32_bf16 v[62:65], v[150:153], v[198:201], v[62:65]
	v_mfma_f32_16x16x32_bf16 v[58:61], v[170:173], v[198:201], v[58:61]
	v_mfma_f32_16x16x32_bf16 v[46:49], v[150:153], v[222:225], v[46:49]
	v_mfma_f32_16x16x32_bf16 v[42:45], v[170:173], v[222:225], v[42:45]
	v_mfma_f32_16x16x32_bf16 v[30:33], v[150:153], v[230:233], v[30:33]
	v_mfma_f32_16x16x32_bf16 v[26:29], v[170:173], v[230:233], v[26:29]
	v_mfma_f32_16x16x32_bf16 v[14:17], v[150:153], v[238:241], v[14:17]
	v_mfma_f32_16x16x32_bf16 v[10:13], v[170:173], v[238:241], v[10:13]
	v_mfma_f32_16x16x32_bf16 v[62:65], v[166:169], v[218:221], v[62:65]
	v_mfma_f32_16x16x32_bf16 v[58:61], v[174:177], v[218:221], v[58:61]
	v_mfma_f32_16x16x32_bf16 v[46:49], v[166:169], v[226:229], v[46:49]
	v_mfma_f32_16x16x32_bf16 v[42:45], v[174:177], v[226:229], v[42:45]
	v_mfma_f32_16x16x32_bf16 v[30:33], v[166:169], v[234:237], v[30:33]
	v_mfma_f32_16x16x32_bf16 v[26:29], v[174:177], v[234:237], v[26:29]
	v_mfma_f32_16x16x32_bf16 v[14:17], v[166:169], v[242:245], v[14:17]
	v_mfma_f32_16x16x32_bf16 v[10:13], v[174:177], v[242:245], v[10:13]
	v_mfma_f32_16x16x32_bf16 v[54:57], v[178:181], v[198:201], v[54:57]
	v_mfma_f32_16x16x32_bf16 v[50:53], v[186:189], v[198:201], v[50:53]
	v_mfma_f32_16x16x32_bf16 v[38:41], v[178:181], v[222:225], v[38:41]
	v_mfma_f32_16x16x32_bf16 v[34:37], v[186:189], v[222:225], v[34:37]
	v_mfma_f32_16x16x32_bf16 v[22:25], v[178:181], v[230:233], v[22:25]
	v_mfma_f32_16x16x32_bf16 v[18:21], v[186:189], v[230:233], v[18:21]
	v_mfma_f32_16x16x32_bf16 v[6:9], v[178:181], v[238:241], v[6:9]
	v_mfma_f32_16x16x32_bf16 v[2:5], v[186:189], v[238:241], v[2:5]
	v_mfma_f32_16x16x32_bf16 v[54:57], v[182:185], v[218:221], v[54:57]
	v_mfma_f32_16x16x32_bf16 v[50:53], v[190:193], v[218:221], v[50:53]
	v_mfma_f32_16x16x32_bf16 v[38:41], v[182:185], v[226:229], v[38:41]
	v_mfma_f32_16x16x32_bf16 v[34:37], v[190:193], v[226:229], v[34:37]
	v_mfma_f32_16x16x32_bf16 v[22:25], v[182:185], v[234:237], v[22:25]
	v_mfma_f32_16x16x32_bf16 v[18:21], v[190:193], v[234:237], v[18:21]
	v_mfma_f32_16x16x32_bf16 v[6:9], v[182:185], v[242:245], v[6:9]
	v_mfma_f32_16x16x32_bf16 v[2:5], v[190:193], v[242:245], v[2:5]
	s_setprio 0
	s_barrier
	s_add_i32 s74, 0, 0x18000
	v_add_u32_e32 v0, s74, v149
	s_add_i32 s75, 0, 0x1c000
	ds_read_b128 v[150:153], v0
	ds_read_b128 v[166:169], v0 offset:1024
	ds_read_b128 v[170:173], v0 offset:2048
	ds_read_b128 v[174:177], v0 offset:3072
	v_add_u32_e32 v0, s75, v149
	ds_read_b128 v[178:181], v0
	ds_read_b128 v[182:185], v0 offset:1024
	ds_read_b128 v[186:189], v0 offset:2048
	ds_read_b128 v[190:193], v0 offset:3072
	s_add_u32 s16, s16, 0x40000
	s_addc_u32 s17, s17, 0
	s_mov_b32 m0, s38
	v_lshl_add_u64 v[204:205], s[16:17], 0, v[130:131]
	ds_read_b128 v[198:201], v164 offset:32768
	ds_read_b128 v[218:221], v164 offset:33792
	ds_read_b128 v[222:225], v164 offset:34816
	ds_read_b128 v[226:229], v164 offset:35840
	ds_read_b128 v[230:233], v164 offset:36864
	ds_read_b128 v[234:237], v164 offset:37888
	ds_read_b128 v[238:241], v164 offset:38912
	ds_read_b128 v[242:245], v164 offset:39936
	global_load_lds_dwordx4 v[204:205], off
	v_lshl_add_u64 v[204:205], s[16:17], 0, v[134:135]
	s_mov_b32 m0, s39
	s_nop 0
	global_load_lds_dwordx4 v[204:205], off
	s_waitcnt vmcnt(8)
	s_waitcnt lgkmcnt(0)
	s_barrier
	s_setprio 1
	s_waitcnt lgkmcnt(0)
	v_mfma_f32_16x16x32_bf16 v[126:129], v[150:153], v[198:201], v[126:129]
	v_mfma_f32_16x16x32_bf16 v[122:125], v[170:173], v[198:201], v[122:125]
	v_mfma_f32_16x16x32_bf16 v[110:113], v[150:153], v[222:225], v[110:113]
	v_mfma_f32_16x16x32_bf16 v[106:109], v[170:173], v[222:225], v[106:109]
	v_mfma_f32_16x16x32_bf16 v[94:97], v[150:153], v[230:233], v[94:97]
	v_mfma_f32_16x16x32_bf16 v[90:93], v[170:173], v[230:233], v[90:93]
	v_mfma_f32_16x16x32_bf16 v[78:81], v[150:153], v[238:241], v[78:81]
	v_mfma_f32_16x16x32_bf16 v[74:77], v[170:173], v[238:241], v[74:77]
	v_mfma_f32_16x16x32_bf16 v[126:129], v[166:169], v[218:221], v[126:129]
	v_mfma_f32_16x16x32_bf16 v[122:125], v[174:177], v[218:221], v[122:125]
	v_mfma_f32_16x16x32_bf16 v[110:113], v[166:169], v[226:229], v[110:113]
	v_mfma_f32_16x16x32_bf16 v[106:109], v[174:177], v[226:229], v[106:109]
	v_mfma_f32_16x16x32_bf16 v[94:97], v[166:169], v[234:237], v[94:97]
	v_mfma_f32_16x16x32_bf16 v[90:93], v[174:177], v[234:237], v[90:93]
	v_mfma_f32_16x16x32_bf16 v[78:81], v[166:169], v[242:245], v[78:81]
	v_mfma_f32_16x16x32_bf16 v[74:77], v[174:177], v[242:245], v[74:77]
	v_mfma_f32_16x16x32_bf16 v[118:121], v[178:181], v[198:201], v[118:121]
	v_mfma_f32_16x16x32_bf16 v[114:117], v[186:189], v[198:201], v[114:117]
	v_mfma_f32_16x16x32_bf16 v[102:105], v[178:181], v[222:225], v[102:105]
	v_mfma_f32_16x16x32_bf16 v[98:101], v[186:189], v[222:225], v[98:101]
	v_mfma_f32_16x16x32_bf16 v[86:89], v[178:181], v[230:233], v[86:89]
	v_mfma_f32_16x16x32_bf16 v[82:85], v[186:189], v[230:233], v[82:85]
	v_mfma_f32_16x16x32_bf16 v[70:73], v[178:181], v[238:241], v[70:73]
	v_mfma_f32_16x16x32_bf16 v[66:69], v[186:189], v[238:241], v[66:69]
	v_mfma_f32_16x16x32_bf16 v[118:121], v[182:185], v[218:221], v[118:121]
	v_mfma_f32_16x16x32_bf16 v[114:117], v[190:193], v[218:221], v[114:117]
	v_mfma_f32_16x16x32_bf16 v[102:105], v[182:185], v[226:229], v[102:105]
	v_mfma_f32_16x16x32_bf16 v[98:101], v[190:193], v[226:229], v[98:101]
	v_mfma_f32_16x16x32_bf16 v[86:89], v[182:185], v[234:237], v[86:89]
	v_mfma_f32_16x16x32_bf16 v[82:85], v[190:193], v[234:237], v[82:85]
	v_mfma_f32_16x16x32_bf16 v[70:73], v[182:185], v[242:245], v[70:73]
	v_mfma_f32_16x16x32_bf16 v[66:69], v[190:193], v[242:245], v[66:69]
	s_setprio 0
	s_barrier
; #define PG8_STAGE(bufoff, gbase, voff) do { _Pragma("unroll") for (int _i = 0; _i < 2; ++_i) \
;         __builtin_amdgcn_global_load_lds((const unsigned*)((const char*)(gbase) + (voff)[_i]), (PG8_LAS unsigned*)(lds + (bufoff) + ldsw + _i * 8192), 16, 0, 0); } while (0)
; #define PG8_LDA(dst, b, h) do { _Pragma("unroll") for (int m = 0; m < 4; ++m) _Pragma("unroll") for (int k = 0; k < 2; ++k) dst[m][k] = *(const PG8_LAS bf16x8*)(lds + PG8_SA(b, h) + aoff + m * 2048 + k * 1024); } while (0)
; #define PG8_MMA(ai, bj, At, Bt) do { __builtin_amdgcn_s_setprio(1); _Pragma("unroll") for (int m = 0; m < 4; ++m) _Pragma("unroll") for (int n = 0; n < 2; ++n) _Pragma("unroll") for (int k = 0; k < 2; ++k) \
;         acc[ai][bj][m][n] = __builtin_amdgcn_mfma_f32_16x16x32_bf16(Bt[n][k], At[m][k], acc[ai][bj][m][n], 0, 0, 0); __builtin_amdgcn_s_setprio(0); } while (0)
; #define PG8_WAIT_V(n) asm volatile("s_waitcnt vmcnt(" #n ")" ::: "memory")
; #define PG8_WAIT_L(n) asm volatile("s_waitcnt lgkmcnt(" #n ")" ::: "memory")
; #define PG8_BAR __builtin_amdgcn_s_barrier()
; #define PG8_SCHED __builtin_amdgcn_sched_barrier(0)
; template <class Epi, class Sched, bool ALIGN_EPI = false, bool SP2 = false>
; __device__ __forceinline__ void gemm_phase(PG8_LAS unsigned char* lds, const Gemm g, const Sched& S, const Epi& E, int wv) {
;     ...
;         for (int t = 0; t < nt; t += 2) {
;             const bool last = (t == nt - 2);
;     ...
;             PG8_LDA(At, 1, 1); PG8_STAGE(PG8_SB(1, 0), b3, voffB); PG8_STAGE(PG8_SB(1, 1), b3 + hstepB, voffB); PG8_STAGE(PG8_SA(1, 0), a3, voffA);
;             PG8_WAIT_V(8); PG8_WAIT_L(0); PG8_BAR; PG8_MMA(1, 0, At, B0); PG8_MMA(1, 1, At, B1); PG8_BAR; PG8_SCHED;
	s_add_i32 s16, s74, s25
	v_lshl_add_u64 v[154:155], v[154:155], 0, s[20:21]
	s_mov_b32 m0, s16
	ds_read_b128 v[198:201], v164 offset:49152
	ds_read_b128 v[218:221], v164 offset:50176
	ds_read_b128 v[222:225], v164 offset:51200
	ds_read_b128 v[226:229], v164 offset:52224
	ds_read_b128 v[230:233], v164 offset:53248
	ds_read_b128 v[234:237], v164 offset:54272
	ds_read_b128 v[238:241], v164 offset:55296
	ds_read_b128 v[242:245], v164 offset:56320
	global_load_lds_dwordx4 v[154:155], off
	s_add_i32 m0, s16, 0x2000
	s_add_u32 s14, s14, 0x40080
	v_lshl_add_u64 v[154:155], v[194:195], 0, s[20:21]
	s_addc_u32 s15, s15, 0
	s_add_i32 s16, s75, s25
	global_load_lds_dwordx4 v[154:155], off
	v_lshl_add_u64 v[154:155], s[14:15], 0, v[132:133]
	s_mov_b32 m0, s16
	s_nop 0
	global_load_lds_dwordx4 v[154:155], off
	v_lshl_add_u64 v[154:155], s[14:15], 0, v[136:137]
	s_add_i32 m0, s16, 0x2000
	s_nop 0
	global_load_lds_dwordx4 v[154:155], off
	v_lshl_add_u64 v[154:155], v[196:197], 0, s[20:21]
	s_mov_b32 m0, s41
	s_nop 0
	global_load_lds_dwordx4 v[154:155], off
	v_lshl_add_u64 v[154:155], v[202:203], 0, s[20:21]
	s_mov_b32 m0, s42
	s_nop 0
	global_load_lds_dwordx4 v[154:155], off
	s_waitcnt vmcnt(8)
	s_waitcnt lgkmcnt(0)
	s_barrier
	s_setprio 1
	s_waitcnt lgkmcnt(0)
	v_mfma_f32_16x16x32_bf16 v[62:65], v[150:153], v[198:201], v[62:65]
	v_mfma_f32_16x16x32_bf16 v[58:61], v[170:173], v[198:201], v[58:61]
	v_mfma_f32_16x16x32_bf16 v[46:49], v[150:153], v[222:225], v[46:49]
	v_mfma_f32_16x16x32_bf16 v[42:45], v[170:173], v[222:225], v[42:45]
	v_mfma_f32_16x16x32_bf16 v[30:33], v[150:153], v[230:233], v[30:33]
	v_mfma_f32_16x16x32_bf16 v[26:29], v[170:173], v[230:233], v[26:29]
	v_mfma_f32_16x16x32_bf16 v[14:17], v[150:153], v[238:241], v[14:17]
	v_mfma_f32_16x16x32_bf16 v[10:13], v[170:173], v[238:241], v[10:13]
	v_mfma_f32_16x16x32_bf16 v[62:65], v[166:169], v[218:221], v[62:65]
	v_mfma_f32_16x16x32_bf16 v[58:61], v[174:177], v[218:221], v[58:61]
	v_mfma_f32_16x16x32_bf16 v[46:49], v[166:169], v[226:229], v[46:49]
	v_mfma_f32_16x16x32_bf16 v[42:45], v[174:177], v[226:229], v[42:45]
	v_mfma_f32_16x16x32_bf16 v[30:33], v[166:169], v[234:237], v[30:33]
	v_mfma_f32_16x16x32_bf16 v[26:29], v[174:177], v[234:237], v[26:29]
	v_mfma_f32_16x16x32_bf16 v[14:17], v[166:169], v[242:245], v[14:17]
	v_mfma_f32_16x16x32_bf16 v[10:13], v[174:177], v[242:245], v[10:13]
	v_mfma_f32_16x16x32_bf16 v[54:57], v[178:181], v[198:201], v[54:57]
	v_mfma_f32_16x16x32_bf16 v[50:53], v[186:189], v[198:201], v[50:53]
	v_mfma_f32_16x16x32_bf16 v[38:41], v[178:181], v[222:225], v[38:41]
	v_mfma_f32_16x16x32_bf16 v[34:37], v[186:189], v[222:225], v[34:37]
	v_mfma_f32_16x16x32_bf16 v[22:25], v[178:181], v[230:233], v[22:25]
	v_mfma_f32_16x16x32_bf16 v[18:21], v[186:189], v[230:233], v[18:21]
	v_mfma_f32_16x16x32_bf16 v[6:9], v[178:181], v[238:241], v[6:9]
	v_mfma_f32_16x16x32_bf16 v[2:5], v[186:189], v[238:241], v[2:5]
	v_mfma_f32_16x16x32_bf16 v[54:57], v[182:185], v[218:221], v[54:57]
	v_mfma_f32_16x16x32_bf16 v[50:53], v[190:193], v[218:221], v[50:53]
	v_mfma_f32_16x16x32_bf16 v[38:41], v[182:185], v[226:229], v[38:41]
	v_mfma_f32_16x16x32_bf16 v[34:37], v[190:193], v[226:229], v[34:37]
	v_mfma_f32_16x16x32_bf16 v[22:25], v[182:185], v[234:237], v[22:25]
	v_mfma_f32_16x16x32_bf16 v[18:21], v[190:193], v[234:237], v[18:21]
	v_mfma_f32_16x16x32_bf16 v[6:9], v[182:185], v[242:245], v[6:9]
	v_mfma_f32_16x16x32_bf16 v[2:5], v[190:193], v[242:245], v[2:5]
	s_setprio 0
	s_barrier
	s_add_i32 s73, s73, 2
	s_add_u32 s12, s12, 0x100
	s_addc_u32 s13, s13, 0
	s_add_u32 s69, s69, 0x100
	s_addc_u32 s72, s72, 0
	s_cmp_gt_u32 s73, 13
	s_cbranch_scc0 .LBB0_358
	s_and_b64 vcc, exec, s[8:9]
	s_cbranch_vccz .LBB0_361
	s_barrier
